# EpiWin (P3): the 8 ss1 row loads hoisted to the epilogue top with counted vmcnt(7+k) waits
# speedup vs baseline: 1.0009x; 1.0009x over previous
; __device__ __forceinline__ float sigmoidf_(float x) { return __builtin_amdgcn_rcpf(1.f + __builtin_amdgcn_exp2f(-x * LOG2E)); }
; __device__ __forceinline__ u32x4 pack8(f32x4 a, f32x4 b) { u32x4 w; w.x = pk2(a[0], a[1]); w.y = pk2(a[2], a[3]); w.z = pk2(b[0], b[1]); w.w = pk2(b[2], b[3]); return w; }
; __device__ __forceinline__ float dot8(f32x4 a, f32x4 b) { return (a[0] * a[0] + a[1] * a[1]) + (a[2] * a[2] + a[3] * a[3]) + (b[0] * b[0] + b[1] * b[1]) + (b[2] * b[2] + b[3] * b[3]); }
; __device__ __forceinline__ float red_fq(float s) { s += __shfl_xor(s, 16); s += __shfl_xor(s, 32); return s; }
;     __device__ __forceinline__ void operator()(AccRef acc, const Unit& u, int wr, int wc, int fr, int fq) const {
;     ...
;             const float rs = __builtin_amdgcn_rsqf(ss1[row] * (1.f / 1024.f) + EPS);
;             f32x4 v[2][2];
;             _Pragma("unroll") for (int bj = 0; bj < 2; ++bj) { v[bj][0] = acc[ai][bj][m][0] * rs; v[bj][1] = acc[ai][bj][m][1] * rs; }
;             if (pn < 3) {
;                 _Pragma("unroll") for (int bj = 0; bj < 2; ++bj) *(u32x4*)(ZA + (size_t)row * 768 + pn * 256 + bj * 128 + cw) = pack8(v[bj][0], v[bj][1]);
;                 float s = dot8(v[0][0], v[0][1]); if (pn != 1) s += dot8(v[1][0], v[1][1]);
;                 s = red_fq(s); if (fq == 0) unsafeAtomicAdd((pn == 2 ? sskv : ssq) + row, s);
;             } else if (pn < 7) {
;                 _Pragma("unroll") for (int bj = 0; bj < 2; ++bj) *(u32x4*)(ZRX + (size_t)row * 1024 + (pn - 3) * 256 + bj * 128 + cw) = pack8(v[bj][0], v[bj][1]);
;             } else if (pn < 11) {
;                 _Pragma("unroll") for (int bj = 0; bj < 2; ++bj) { _Pragma("unroll") for (int n = 0; n < 2; ++n) _Pragma("unroll") for (int i = 0; i < 4; ++i) v[bj][n][i] = gelu_tanh(v[bj][n][i]);
;                     *(u32x4*)(ZRG + (size_t)row * 1024 + (pn - 7) * 256 + bj * 128 + cw) = pack8(v[bj][0], v[bj][1]); }
;             } else {
;                 _Pragma("unroll") for (int bj = 0; bj < 2; ++bj) { unsigned w[2];
;                     _Pragma("unroll") for (int n = 0; n < 2; ++n) { unsigned q = 0; _Pragma("unroll") for (int i = 0; i < 4; ++i) { const unsigned b = (unsigned)(sigmoidf_(v[bj][n][i]) * 255.f + 0.5f); q |= (b > 255u ? 255u : b) << (8 * i); } w[n] = q; }
;                     *(u32x2*)(ZG8 + (size_t)row * 2048 + (pn - 11) * 256 + bj * 128 + cw) = (u32x2){w[0], w[1]}; }
.LBB0_438:
	v_lshl_add_u32 v140, s10, 8, v149
	v_ashrrev_i32_e32 v141, 31, v140
	v_lshl_add_u64 v[142:143], v[140:141], 2, s[84:85]
	global_load_dword v200, v[142:143], off
	global_load_dword v201, v[142:143], off offset:64
	global_load_dword v202, v[142:143], off offset:128
	global_load_dword v203, v[142:143], off offset:192
	global_load_dword v204, v[142:143], off offset:512
	global_load_dword v205, v[142:143], off offset:576
	global_load_dword v206, v[142:143], off offset:640
	global_load_dword v207, v[142:143], off offset:704
	s_cmp_gt_i32 s8, 2
	s_cselect_b64 s[94:95], -1, 0
	s_cmp_gt_u32 s8, 6
	s_cselect_b64 s[12:13], -1, 0
	s_cmp_gt_u32 s8, 10
	s_cselect_b64 s[78:79], -1, 0
	s_lshl_b32 s76, s8, 8
	s_add_i32 s0, s76, 0xfffff500
	s_cmp_lg_u32 s8, 1
	s_cselect_b64 s[10:11], -1, 0
	s_cmp_eq_u32 s8, 2
	s_mov_b32 s77, s1
	s_mov_b64 s[16:17], -1
	s_cselect_b64 s[74:75], -1, 0
	s_and_b64 vcc, exec, s[94:95]
	s_waitcnt vmcnt(7)
	v_fmamk_f32 v134, v200, 0x3a800000, v155
	v_rsq_f32_e32 v134, v134
	s_nop 0
	v_pk_mul_f32 v[128:129], v[128:129], v[134:135] op_sel_hi:[1,0]
	v_pk_mul_f32 v[126:127], v[126:127], v[134:135] op_sel_hi:[1,0]
	v_pk_mul_f32 v[124:125], v[124:125], v[134:135] op_sel_hi:[1,0]
	v_pk_mul_f32 v[122:123], v[122:123], v[134:135] op_sel_hi:[1,0]
	v_pk_mul_f32 v[120:121], v[120:121], v[134:135] op_sel_hi:[1,0]
	v_pk_mul_f32 v[118:119], v[118:119], v[134:135] op_sel_hi:[1,0]
	v_pk_mul_f32 v[116:117], v[116:117], v[134:135] op_sel_hi:[1,0]
	v_pk_mul_f32 v[114:115], v[114:115], v[134:135] op_sel_hi:[1,0]
	s_cbranch_vccz .LBB0_448
	v_lshlrev_b64 v[144:145], 11, v[140:141]
	s_mov_b64 s[8:9], -1
	s_and_b64 vcc, exec, s[12:13]
	s_cbranch_vccz .LBB0_445
	s_andn2_b64 vcc, exec, s[78:79]
	s_cbranch_vccnz .LBB0_442
	v_mul_f32_e32 v134, 0xbfb8aa3b, v126
	v_mul_f32_e32 v157, 0xbfb8aa3b, v127
	v_exp_f32_e32 v134, v134
	v_exp_f32_e32 v157, v157
	v_mul_f32_e32 v158, 0xbfb8aa3b, v129
	v_exp_f32_e32 v158, v158
	v_add_f32_e32 v134, 1.0, v134
	v_add_f32_e32 v157, 1.0, v157
	v_rcp_f32_e32 v134, v134
	v_rcp_f32_e32 v157, v157
	v_add_f32_e32 v158, 1.0, v158
	v_rcp_f32_e32 v158, v158
	v_fma_f32 v134, v134, s51, 0.5
	v_fma_f32 v157, v157, s51, 0.5
	v_cvt_u32_f32_e32 v134, v134
	v_cvt_u32_f32_e32 v157, v157
	v_fma_f32 v158, v158, s51, 0.5
	v_cvt_u32_f32_e32 v158, v158
	v_min_u32_e32 v134, 0xff, v134
	v_min_u32_e32 v157, 0xff, v157
	v_lshl_or_b32 v134, v157, 8, v134
	v_mul_f32_e32 v157, 0xbfb8aa3b, v128
	v_exp_f32_e32 v157, v157
	v_min_u32_sdwa v158, v158, s58 dst_sel:BYTE_3 dst_unused:UNUSED_PAD src0_sel:DWORD src1_sel:DWORD
	v_mul_f32_e32 v159, 0xbfb8aa3b, v125
	v_exp_f32_e32 v159, v159
	v_add_f32_e32 v157, 1.0, v157
	v_rcp_f32_e32 v157, v157
	v_lshl_add_u64 v[160:161], s[22:23], 0, v[144:145]
	v_add_f32_e32 v159, 1.0, v159
	v_rcp_f32_e32 v159, v159
	v_fma_f32 v157, v157, s51, 0.5
	v_cvt_u32_f32_e32 v157, v157
	v_lshl_add_u64 v[160:161], v[160:161], 0, s[0:1]
	v_fma_f32 v159, v159, s51, 0.5
	v_cvt_u32_f32_e32 v159, v159
	v_min_u32_sdwa v157, v157, s58 dst_sel:WORD_1 dst_unused:UNUSED_PAD src0_sel:DWORD src1_sel:DWORD
	v_lshl_add_u64 v[160:161], v[160:161], 0, v[130:131]
	v_or3_b32 v158, v134, v157, v158
	v_mul_f32_e32 v134, 0xbfb8aa3b, v122
	v_mul_f32_e32 v157, 0xbfb8aa3b, v123
	v_exp_f32_e32 v134, v134
	v_exp_f32_e32 v157, v157
	v_min_u32_sdwa v159, v159, s58 dst_sel:BYTE_3 dst_unused:UNUSED_PAD src0_sel:DWORD src1_sel:DWORD
	s_mov_b64 s[8:9], 0
	v_add_f32_e32 v134, 1.0, v134
	v_add_f32_e32 v157, 1.0, v157
	v_rcp_f32_e32 v134, v134
	v_rcp_f32_e32 v157, v157
	v_fma_f32 v134, v134, s51, 0.5
	v_fma_f32 v157, v157, s51, 0.5
	v_cvt_u32_f32_e32 v134, v134
	v_cvt_u32_f32_e32 v157, v157
	v_min_u32_e32 v134, 0xff, v134
	v_min_u32_e32 v157, 0xff, v157
	v_lshl_or_b32 v134, v157, 8, v134
	v_mul_f32_e32 v157, 0xbfb8aa3b, v124
	v_exp_f32_e32 v157, v157
	s_nop 0
	v_add_f32_e32 v157, 1.0, v157
	v_rcp_f32_e32 v157, v157
	s_nop 0
	v_fma_f32 v157, v157, s51, 0.5
	v_cvt_u32_f32_e32 v157, v157
	v_min_u32_sdwa v157, v157, s58 dst_sel:WORD_1 dst_unused:UNUSED_PAD src0_sel:DWORD src1_sel:DWORD
	s_nop 0
	v_or3_b32 v159, v134, v157, v159
	v_mul_f32_e32 v134, 0xbfb8aa3b, v118
	v_mul_f32_e32 v157, 0xbfb8aa3b, v119
	v_exp_f32_e32 v134, v134
	v_exp_f32_e32 v157, v157
	global_store_dwordx2 v[160:161], v[158:159], off
	v_mul_f32_e32 v158, 0xbfb8aa3b, v121
	v_add_f32_e32 v134, 1.0, v134
	v_add_f32_e32 v157, 1.0, v157
	v_rcp_f32_e32 v134, v134
	v_rcp_f32_e32 v157, v157
	v_exp_f32_e32 v158, v158
	v_mul_f32_e32 v159, 0xbfb8aa3b, v117
	v_fma_f32 v134, v134, s51, 0.5
	v_fma_f32 v157, v157, s51, 0.5
	v_cvt_u32_f32_e32 v134, v134
	v_cvt_u32_f32_e32 v157, v157
	v_add_f32_e32 v158, 1.0, v158
	v_rcp_f32_e32 v158, v158
	v_min_u32_e32 v134, 0xff, v134
	v_min_u32_e32 v157, 0xff, v157
	v_lshl_or_b32 v134, v157, 8, v134
	v_mul_f32_e32 v157, 0xbfb8aa3b, v120
	v_exp_f32_e32 v157, v157
	v_fma_f32 v158, v158, s51, 0.5
	v_cvt_u32_f32_e32 v158, v158
	v_exp_f32_e32 v159, v159
	v_add_f32_e32 v157, 1.0, v157
	v_rcp_f32_e32 v157, v157
	v_min_u32_sdwa v158, v158, s58 dst_sel:BYTE_3 dst_unused:UNUSED_PAD src0_sel:DWORD src1_sel:DWORD
	v_add_f32_e32 v159, 1.0, v159
	v_rcp_f32_e32 v159, v159
	v_fma_f32 v157, v157, s51, 0.5
	v_cvt_u32_f32_e32 v157, v157
	v_fma_f32 v159, v159, s51, 0.5
	v_cvt_u32_f32_e32 v159, v159
	v_min_u32_sdwa v157, v157, s58 dst_sel:WORD_1 dst_unused:UNUSED_PAD src0_sel:DWORD src1_sel:DWORD
	v_min_u32_sdwa v159, v159, s58 dst_sel:BYTE_3 dst_unused:UNUSED_PAD src0_sel:DWORD src1_sel:DWORD
	v_or3_b32 v158, v134, v157, v158
	v_mul_f32_e32 v134, 0xbfb8aa3b, v114
	v_mul_f32_e32 v157, 0xbfb8aa3b, v115
	v_exp_f32_e32 v134, v134
	v_exp_f32_e32 v157, v157
	v_add_f32_e32 v134, 1.0, v134
	v_add_f32_e32 v157, 1.0, v157
	v_rcp_f32_e32 v134, v134
	v_rcp_f32_e32 v157, v157
	v_fma_f32 v134, v134, s51, 0.5
	v_fma_f32 v157, v157, s51, 0.5
	v_cvt_u32_f32_e32 v134, v134
	v_cvt_u32_f32_e32 v157, v157
	v_min_u32_e32 v134, 0xff, v134
	v_min_u32_e32 v157, 0xff, v157
	v_lshl_or_b32 v134, v157, 8, v134
	v_mul_f32_e32 v157, 0xbfb8aa3b, v116
	v_exp_f32_e32 v157, v157
	s_nop 0
	v_add_f32_e32 v157, 1.0, v157
	v_rcp_f32_e32 v157, v157
	s_nop 0
	v_fma_f32 v157, v157, s51, 0.5
	v_cvt_u32_f32_e32 v157, v157
	v_min_u32_sdwa v157, v157, s58 dst_sel:WORD_1 dst_unused:UNUSED_PAD src0_sel:DWORD src1_sel:DWORD
	s_nop 0
	v_or3_b32 v159, v134, v157, v159
	global_store_dwordx2 v[160:161], v[158:159], off offset:128

; __device__ __forceinline__ float sigmoidf_(float x) { return __builtin_amdgcn_rcpf(1.f + __builtin_amdgcn_exp2f(-x * LOG2E)); }
; __device__ __forceinline__ u32x4 pack8(f32x4 a, f32x4 b) { u32x4 w; w.x = pk2(a[0], a[1]); w.y = pk2(a[2], a[3]); w.z = pk2(b[0], b[1]); w.w = pk2(b[2], b[3]); return w; }
; __device__ __forceinline__ float dot8(f32x4 a, f32x4 b) { return (a[0] * a[0] + a[1] * a[1]) + (a[2] * a[2] + a[3] * a[3]) + (b[0] * b[0] + b[1] * b[1]) + (b[2] * b[2] + b[3] * b[3]); }
; __device__ __forceinline__ float red_fq(float s) { s += __shfl_xor(s, 16); s += __shfl_xor(s, 32); return s; }
;     __device__ __forceinline__ void operator()(AccRef acc, const Unit& u, int wr, int wc, int fr, int fq) const {
;     ...
;             const float rs = __builtin_amdgcn_rsqf(ss1[row] * (1.f / 1024.f) + EPS);
;             f32x4 v[2][2];
;             _Pragma("unroll") for (int bj = 0; bj < 2; ++bj) { v[bj][0] = acc[ai][bj][m][0] * rs; v[bj][1] = acc[ai][bj][m][1] * rs; }
;             if (pn < 3) {
;                 _Pragma("unroll") for (int bj = 0; bj < 2; ++bj) *(u32x4*)(ZA + (size_t)row * 768 + pn * 256 + bj * 128 + cw) = pack8(v[bj][0], v[bj][1]);
;                 float s = dot8(v[0][0], v[0][1]); if (pn != 1) s += dot8(v[1][0], v[1][1]);
;                 s = red_fq(s); if (fq == 0) unsafeAtomicAdd((pn == 2 ? sskv : ssq) + row, s);
;             } else if (pn < 7) {
;                 _Pragma("unroll") for (int bj = 0; bj < 2; ++bj) *(u32x4*)(ZRX + (size_t)row * 1024 + (pn - 3) * 256 + bj * 128 + cw) = pack8(v[bj][0], v[bj][1]);
;             } else if (pn < 11) {
;                 _Pragma("unroll") for (int bj = 0; bj < 2; ++bj) { _Pragma("unroll") for (int n = 0; n < 2; ++n) _Pragma("unroll") for (int i = 0; i < 4; ++i) v[bj][n][i] = gelu_tanh(v[bj][n][i]);
;                     *(u32x4*)(ZRG + (size_t)row * 1024 + (pn - 7) * 256 + bj * 128 + cw) = pack8(v[bj][0], v[bj][1]); }
;             } else {
;                 _Pragma("unroll") for (int bj = 0; bj < 2; ++bj) { unsigned w[2];
;                     _Pragma("unroll") for (int n = 0; n < 2; ++n) { unsigned q = 0; _Pragma("unroll") for (int i = 0; i < 4; ++i) { const unsigned b = (unsigned)(sigmoidf_(v[bj][n][i]) * 255.f + 0.5f); q |= (b > 255u ? 255u : b) << (8 * i); } w[n] = q; }
;                     *(u32x2*)(ZG8 + (size_t)row * 2048 + (pn - 11) * 256 + bj * 128 + cw) = (u32x2){w[0], w[1]}; }
.LBB0_454:
	s_nop 0
	v_or_b32_e32 v114, 16, v140
	s_waitcnt lgkmcnt(0)
	v_ashrrev_i32_e32 v115, 31, v114
	s_mov_b64 s[16:17], -1
	s_andn2_b64 vcc, exec, s[94:95]
	s_waitcnt vmcnt(8)
	v_fmamk_f32 v116, v201, 0x3a800000, v155
	v_rsq_f32_e32 v116, v116
	s_nop 0
	v_pk_mul_f32 v[112:113], v[112:113], v[116:117] op_sel_hi:[1,0]
	v_pk_mul_f32 v[110:111], v[110:111], v[116:117] op_sel_hi:[1,0]
	v_pk_mul_f32 v[108:109], v[108:109], v[116:117] op_sel_hi:[1,0]
	v_pk_mul_f32 v[106:107], v[106:107], v[116:117] op_sel_hi:[1,0]
	v_pk_mul_f32 v[104:105], v[104:105], v[116:117] op_sel_hi:[1,0]
	v_pk_mul_f32 v[102:103], v[102:103], v[116:117] op_sel_hi:[1,0]
	v_pk_mul_f32 v[100:101], v[100:101], v[116:117] op_sel_hi:[1,0]
	v_pk_mul_f32 v[98:99], v[98:99], v[116:117] op_sel_hi:[1,0]
	v_cndmask_b32_e64 v116, 0, 1, s[94:95]
	v_cmp_ne_u32_e64 s[10:11], 1, v116
	v_cndmask_b32_e64 v116, 0, 1, s[12:13]
	v_cmp_ne_u32_e64 s[12:13], 1, v116
	s_cbranch_vccnz .LBB0_464
	v_lshlrev_b64 v[116:117], 11, v[114:115]
	s_and_b64 vcc, exec, s[12:13]
	s_cbranch_vccnz .LBB0_461
	s_andn2_b64 vcc, exec, s[78:79]
	s_cbranch_vccnz .LBB0_458
	v_mul_f32_e32 v115, 0xbfb8aa3b, v110
	v_mul_f32_e32 v118, 0xbfb8aa3b, v111
	v_exp_f32_e32 v115, v115
	v_exp_f32_e32 v118, v118
	v_mul_f32_e32 v119, 0xbfb8aa3b, v113
	v_exp_f32_e32 v119, v119
	v_add_f32_e32 v115, 1.0, v115
	v_add_f32_e32 v118, 1.0, v118
	v_rcp_f32_e32 v115, v115
	v_rcp_f32_e32 v118, v118
	v_add_f32_e32 v119, 1.0, v119
	v_rcp_f32_e32 v119, v119
	v_fma_f32 v115, v115, s51, 0.5
	v_fma_f32 v118, v118, s51, 0.5
	v_cvt_u32_f32_e32 v115, v115
	v_cvt_u32_f32_e32 v118, v118
	v_fma_f32 v119, v119, s51, 0.5
	v_cvt_u32_f32_e32 v119, v119
	v_min_u32_e32 v115, 0xff, v115
	v_min_u32_e32 v118, 0xff, v118
	v_lshl_or_b32 v115, v118, 8, v115
	v_mul_f32_e32 v118, 0xbfb8aa3b, v112
	v_exp_f32_e32 v118, v118
	v_min_u32_sdwa v119, v119, s58 dst_sel:BYTE_3 dst_unused:UNUSED_PAD src0_sel:DWORD src1_sel:DWORD
	v_mul_f32_e32 v120, 0xbfb8aa3b, v109
	v_exp_f32_e32 v120, v120
	v_add_f32_e32 v118, 1.0, v118
	v_rcp_f32_e32 v118, v118
	v_mul_f32_e32 v122, 0xbfb8aa3b, v101
	v_add_f32_e32 v120, 1.0, v120
	v_rcp_f32_e32 v120, v120
	v_fma_f32 v118, v118, s51, 0.5
	v_cvt_u32_f32_e32 v118, v118
	v_exp_f32_e32 v122, v122
	v_fma_f32 v120, v120, s51, 0.5
	v_cvt_u32_f32_e32 v120, v120
	v_min_u32_sdwa v118, v118, s58 dst_sel:WORD_1 dst_unused:UNUSED_PAD src0_sel:DWORD src1_sel:DWORD
	v_add_f32_e32 v122, 1.0, v122
	v_or3_b32 v118, v115, v118, v119
	v_mul_f32_e32 v115, 0xbfb8aa3b, v106
	v_mul_f32_e32 v119, 0xbfb8aa3b, v107
	v_exp_f32_e32 v115, v115
	v_exp_f32_e32 v119, v119
	v_min_u32_sdwa v120, v120, s58 dst_sel:BYTE_3 dst_unused:UNUSED_PAD src0_sel:DWORD src1_sel:DWORD
	v_rcp_f32_e32 v122, v122
	v_add_f32_e32 v115, 1.0, v115
	v_add_f32_e32 v119, 1.0, v119
	v_rcp_f32_e32 v115, v115
	v_rcp_f32_e32 v119, v119
	v_fma_f32 v122, v122, s51, 0.5
	v_cvt_u32_f32_e32 v122, v122
	v_fma_f32 v115, v115, s51, 0.5
	v_fma_f32 v119, v119, s51, 0.5
	v_cvt_u32_f32_e32 v115, v115
	v_cvt_u32_f32_e32 v119, v119
	v_min_u32_sdwa v122, v122, s58 dst_sel:BYTE_3 dst_unused:UNUSED_PAD src0_sel:DWORD src1_sel:DWORD
	s_mov_b64 s[16:17], 0
	v_min_u32_e32 v115, 0xff, v115
	v_min_u32_e32 v119, 0xff, v119
	v_lshl_or_b32 v115, v119, 8, v115
	v_mul_f32_e32 v119, 0xbfb8aa3b, v108
	v_exp_f32_e32 v119, v119
	s_nop 0
	v_add_f32_e32 v119, 1.0, v119
	v_rcp_f32_e32 v119, v119
	s_nop 0
	v_fma_f32 v119, v119, s51, 0.5
	v_cvt_u32_f32_e32 v119, v119
	v_min_u32_sdwa v119, v119, s58 dst_sel:WORD_1 dst_unused:UNUSED_PAD src0_sel:DWORD src1_sel:DWORD
	s_nop 0
	v_or3_b32 v119, v115, v119, v120
	v_lshl_add_u64 v[120:121], s[22:23], 0, v[116:117]
	v_lshl_add_u64 v[120:121], v[120:121], 0, s[0:1]
	v_lshl_add_u64 v[120:121], v[120:121], 0, v[130:131]
	global_store_dwordx2 v[120:121], v[118:119], off
	v_mul_f32_e32 v115, 0xbfb8aa3b, v102
	v_mul_f32_e32 v118, 0xbfb8aa3b, v103
	v_exp_f32_e32 v115, v115
	v_exp_f32_e32 v118, v118
	v_mul_f32_e32 v119, 0xbfb8aa3b, v105
	v_exp_f32_e32 v119, v119
	v_add_f32_e32 v115, 1.0, v115
	v_add_f32_e32 v118, 1.0, v118
	v_rcp_f32_e32 v115, v115
	v_rcp_f32_e32 v118, v118
	v_add_f32_e32 v119, 1.0, v119
	v_rcp_f32_e32 v119, v119
	v_fma_f32 v115, v115, s51, 0.5
	v_fma_f32 v118, v118, s51, 0.5
	v_cvt_u32_f32_e32 v115, v115
	v_cvt_u32_f32_e32 v118, v118
	v_fma_f32 v119, v119, s51, 0.5
	v_cvt_u32_f32_e32 v119, v119
	v_min_u32_e32 v115, 0xff, v115
	v_min_u32_e32 v118, 0xff, v118
	v_lshl_or_b32 v115, v118, 8, v115
	v_mul_f32_e32 v118, 0xbfb8aa3b, v104
	v_exp_f32_e32 v118, v118
	v_min_u32_sdwa v119, v119, s58 dst_sel:BYTE_3 dst_unused:UNUSED_PAD src0_sel:DWORD src1_sel:DWORD
	v_add_f32_e32 v118, 1.0, v118
	v_rcp_f32_e32 v118, v118
	s_nop 0
	v_fma_f32 v118, v118, s51, 0.5
	v_cvt_u32_f32_e32 v118, v118
	v_min_u32_sdwa v118, v118, s58 dst_sel:WORD_1 dst_unused:UNUSED_PAD src0_sel:DWORD src1_sel:DWORD
	s_nop 0
	v_or3_b32 v118, v115, v118, v119
	v_mul_f32_e32 v115, 0xbfb8aa3b, v98
	v_mul_f32_e32 v119, 0xbfb8aa3b, v99
	v_exp_f32_e32 v115, v115
	v_exp_f32_e32 v119, v119
	v_add_f32_e32 v115, 1.0, v115
	v_add_f32_e32 v119, 1.0, v119
	v_rcp_f32_e32 v115, v115
	v_rcp_f32_e32 v119, v119
	v_fma_f32 v115, v115, s51, 0.5
	v_fma_f32 v119, v119, s51, 0.5
	v_cvt_u32_f32_e32 v115, v115
	v_cvt_u32_f32_e32 v119, v119
	v_min_u32_e32 v115, 0xff, v115
	v_min_u32_e32 v119, 0xff, v119
	v_lshl_or_b32 v115, v119, 8, v115
	v_mul_f32_e32 v119, 0xbfb8aa3b, v100
	v_exp_f32_e32 v119, v119
	s_nop 0
	v_add_f32_e32 v119, 1.0, v119
	v_rcp_f32_e32 v119, v119
	s_nop 0
	v_fma_f32 v119, v119, s51, 0.5
	v_cvt_u32_f32_e32 v119, v119
	v_min_u32_sdwa v119, v119, s58 dst_sel:WORD_1 dst_unused:UNUSED_PAD src0_sel:DWORD src1_sel:DWORD
	s_nop 0
	v_or3_b32 v119, v115, v119, v122
	global_store_dwordx2 v[120:121], v[118:119], off offset:128

; __device__ __forceinline__ float sigmoidf_(float x) { return __builtin_amdgcn_rcpf(1.f + __builtin_amdgcn_exp2f(-x * LOG2E)); }
; #define EPI_ROWS(...) _Pragma("unroll") for (int ai = 0; ai < 2; ++ai) _Pragma("unroll") for (int m = 0; m < 4; ++m) { const int row = row0 + ai * 128 + m * 16; __VA_ARGS__ __builtin_amdgcn_sched_barrier(0); }
; __device__ __forceinline__ float red_fq(float s) { s += __shfl_xor(s, 16); s += __shfl_xor(s, 32); return s; }
;     __device__ __forceinline__ void operator()(AccRef acc, const Unit& u, int wr, int wc, int fr, int fq) const {
;         const int row0 = u.pm * 256 + wr * 64 + fr, cw = wc * 32 + 8 * fq; const int pn = u.pn;
;         EPI_ROWS(
;             const float rs = __builtin_amdgcn_rsqf(ss1[row] * (1.f / 1024.f) + EPS);
;             f32x4 v[2][2];
;             _Pragma("unroll") for (int bj = 0; bj < 2; ++bj) { v[bj][0] = acc[ai][bj][m][0] * rs; v[bj][1] = acc[ai][bj][m][1] * rs; }
;             if (pn < 3) {
;                 _Pragma("unroll") for (int bj = 0; bj < 2; ++bj) *(u32x4*)(ZA + (size_t)row * 768 + pn * 256 + bj * 128 + cw) = pack8(v[bj][0], v[bj][1]);
;                 float s = dot8(v[0][0], v[0][1]); if (pn != 1) s += dot8(v[1][0], v[1][1]);
;                 s = red_fq(s); if (fq == 0) unsafeAtomicAdd((pn == 2 ? sskv : ssq) + row, s);
;             } else if (pn < 7) {
;                 _Pragma("unroll") for (int bj = 0; bj < 2; ++bj) *(u32x4*)(ZRX + (size_t)row * 1024 + (pn - 3) * 256 + bj * 128 + cw) = pack8(v[bj][0], v[bj][1]);
;             } else if (pn < 11) {
;                 _Pragma("unroll") for (int bj = 0; bj < 2; ++bj) { _Pragma("unroll") for (int n = 0; n < 2; ++n) _Pragma("unroll") for (int i = 0; i < 4; ++i) v[bj][n][i] = gelu_tanh(v[bj][n][i]);
;                     *(u32x4*)(ZRG + (size_t)row * 1024 + (pn - 7) * 256 + bj * 128 + cw) = pack8(v[bj][0], v[bj][1]); }
;             } else {
;                 _Pragma("unroll") for (int bj = 0; bj < 2; ++bj) { unsigned w[2];
;                     _Pragma("unroll") for (int n = 0; n < 2; ++n) { unsigned q = 0; _Pragma("unroll") for (int i = 0; i < 4; ++i) { const unsigned b = (unsigned)(sigmoidf_(v[bj][n][i]) * 255.f + 0.5f); q |= (b > 255u ? 255u : b) << (8 * i); } w[n] = q; }
;                     *(u32x2*)(ZG8 + (size_t)row * 2048 + (pn - 11) * 256 + bj * 128 + cw) = (u32x2){w[0], w[1]}; }
.LBB0_470:
	s_nop 0
	s_and_b64 vcc, exec, s[10:11]
	s_mov_b64 s[16:17], -1
	s_waitcnt vmcnt(9)
	v_fmamk_f32 v98, v202, 0x3a800000, v155
	v_rsq_f32_e32 v100, v98
	v_or_b32_e32 v98, 32, v140
	s_waitcnt lgkmcnt(0)
	v_ashrrev_i32_e32 v99, 31, v98
	v_pk_mul_f32 v[96:97], v[96:97], v[100:101] op_sel_hi:[1,0]
	v_pk_mul_f32 v[94:95], v[94:95], v[100:101] op_sel_hi:[1,0]
	v_pk_mul_f32 v[92:93], v[92:93], v[100:101] op_sel_hi:[1,0]
	v_pk_mul_f32 v[90:91], v[90:91], v[100:101] op_sel_hi:[1,0]
	v_pk_mul_f32 v[88:89], v[88:89], v[100:101] op_sel_hi:[1,0]
	v_pk_mul_f32 v[86:87], v[86:87], v[100:101] op_sel_hi:[1,0]
	v_pk_mul_f32 v[84:85], v[84:85], v[100:101] op_sel_hi:[1,0]
	v_pk_mul_f32 v[82:83], v[82:83], v[100:101] op_sel_hi:[1,0]
	s_cbranch_vccnz .LBB0_480
	v_lshlrev_b64 v[100:101], 11, v[98:99]
	s_and_b64 vcc, exec, s[12:13]
	s_cbranch_vccnz .LBB0_477
	s_andn2_b64 vcc, exec, s[78:79]
	s_cbranch_vccnz .LBB0_474
	v_mul_f32_e32 v99, 0xbfb8aa3b, v94
	v_mul_f32_e32 v102, 0xbfb8aa3b, v95
	v_exp_f32_e32 v99, v99
	v_exp_f32_e32 v102, v102
	v_mul_f32_e32 v103, 0xbfb8aa3b, v97
	v_exp_f32_e32 v103, v103
	v_add_f32_e32 v99, 1.0, v99
	v_add_f32_e32 v102, 1.0, v102
	v_rcp_f32_e32 v99, v99
	v_rcp_f32_e32 v102, v102
	v_add_f32_e32 v103, 1.0, v103
	v_rcp_f32_e32 v103, v103
	v_fma_f32 v99, v99, s51, 0.5
	v_fma_f32 v102, v102, s51, 0.5
	v_cvt_u32_f32_e32 v99, v99
	v_cvt_u32_f32_e32 v102, v102
	v_fma_f32 v103, v103, s51, 0.5
	v_cvt_u32_f32_e32 v103, v103
	v_min_u32_e32 v99, 0xff, v99
	v_min_u32_e32 v102, 0xff, v102
	v_lshl_or_b32 v99, v102, 8, v99
	v_mul_f32_e32 v102, 0xbfb8aa3b, v96
	v_exp_f32_e32 v102, v102
	v_min_u32_sdwa v103, v103, s58 dst_sel:BYTE_3 dst_unused:UNUSED_PAD src0_sel:DWORD src1_sel:DWORD
	v_mul_f32_e32 v104, 0xbfb8aa3b, v93
	v_exp_f32_e32 v104, v104
	v_add_f32_e32 v102, 1.0, v102
	v_rcp_f32_e32 v102, v102
	v_mul_f32_e32 v106, 0xbfb8aa3b, v85
	v_add_f32_e32 v104, 1.0, v104
	v_rcp_f32_e32 v104, v104
	v_fma_f32 v102, v102, s51, 0.5
	v_cvt_u32_f32_e32 v102, v102
	v_exp_f32_e32 v106, v106
	v_fma_f32 v104, v104, s51, 0.5
	v_cvt_u32_f32_e32 v104, v104
	v_min_u32_sdwa v102, v102, s58 dst_sel:WORD_1 dst_unused:UNUSED_PAD src0_sel:DWORD src1_sel:DWORD
	v_add_f32_e32 v106, 1.0, v106
	v_or3_b32 v102, v99, v102, v103
	v_mul_f32_e32 v99, 0xbfb8aa3b, v90
	v_mul_f32_e32 v103, 0xbfb8aa3b, v91
	v_exp_f32_e32 v99, v99
	v_exp_f32_e32 v103, v103
	v_min_u32_sdwa v104, v104, s58 dst_sel:BYTE_3 dst_unused:UNUSED_PAD src0_sel:DWORD src1_sel:DWORD
	v_rcp_f32_e32 v106, v106
	v_add_f32_e32 v99, 1.0, v99
	v_add_f32_e32 v103, 1.0, v103
	v_rcp_f32_e32 v99, v99
	v_rcp_f32_e32 v103, v103
	v_fma_f32 v106, v106, s51, 0.5
	v_cvt_u32_f32_e32 v106, v106
	v_fma_f32 v99, v99, s51, 0.5
	v_fma_f32 v103, v103, s51, 0.5
	v_cvt_u32_f32_e32 v99, v99
	v_cvt_u32_f32_e32 v103, v103
	v_min_u32_sdwa v106, v106, s58 dst_sel:BYTE_3 dst_unused:UNUSED_PAD src0_sel:DWORD src1_sel:DWORD
	s_mov_b64 s[16:17], 0
	v_min_u32_e32 v99, 0xff, v99
	v_min_u32_e32 v103, 0xff, v103
	v_lshl_or_b32 v99, v103, 8, v99
	v_mul_f32_e32 v103, 0xbfb8aa3b, v92
	v_exp_f32_e32 v103, v103
	s_nop 0
	v_add_f32_e32 v103, 1.0, v103
	v_rcp_f32_e32 v103, v103
	s_nop 0
	v_fma_f32 v103, v103, s51, 0.5
	v_cvt_u32_f32_e32 v103, v103
	v_min_u32_sdwa v103, v103, s58 dst_sel:WORD_1 dst_unused:UNUSED_PAD src0_sel:DWORD src1_sel:DWORD
	s_nop 0
	v_or3_b32 v103, v99, v103, v104
	v_lshl_add_u64 v[104:105], s[22:23], 0, v[100:101]
	v_lshl_add_u64 v[104:105], v[104:105], 0, s[0:1]
	v_lshl_add_u64 v[104:105], v[104:105], 0, v[130:131]
	global_store_dwordx2 v[104:105], v[102:103], off
	v_mul_f32_e32 v99, 0xbfb8aa3b, v86
	v_mul_f32_e32 v102, 0xbfb8aa3b, v87
	v_exp_f32_e32 v99, v99
	v_exp_f32_e32 v102, v102
	v_mul_f32_e32 v103, 0xbfb8aa3b, v89
	v_exp_f32_e32 v103, v103
	v_add_f32_e32 v99, 1.0, v99
	v_add_f32_e32 v102, 1.0, v102
	v_rcp_f32_e32 v99, v99
	v_rcp_f32_e32 v102, v102
	v_add_f32_e32 v103, 1.0, v103
	v_rcp_f32_e32 v103, v103
	v_fma_f32 v99, v99, s51, 0.5
	v_fma_f32 v102, v102, s51, 0.5
	v_cvt_u32_f32_e32 v99, v99
	v_cvt_u32_f32_e32 v102, v102
	v_fma_f32 v103, v103, s51, 0.5
	v_cvt_u32_f32_e32 v103, v103
	v_min_u32_e32 v99, 0xff, v99
	v_min_u32_e32 v102, 0xff, v102
	v_lshl_or_b32 v99, v102, 8, v99
	v_mul_f32_e32 v102, 0xbfb8aa3b, v88
	v_exp_f32_e32 v102, v102
	v_min_u32_sdwa v103, v103, s58 dst_sel:BYTE_3 dst_unused:UNUSED_PAD src0_sel:DWORD src1_sel:DWORD
	v_add_f32_e32 v102, 1.0, v102
	v_rcp_f32_e32 v102, v102
	s_nop 0
	v_fma_f32 v102, v102, s51, 0.5
	v_cvt_u32_f32_e32 v102, v102
	v_min_u32_sdwa v102, v102, s58 dst_sel:WORD_1 dst_unused:UNUSED_PAD src0_sel:DWORD src1_sel:DWORD
	s_nop 0
	v_or3_b32 v102, v99, v102, v103
	v_mul_f32_e32 v99, 0xbfb8aa3b, v82
	v_mul_f32_e32 v103, 0xbfb8aa3b, v83
	v_exp_f32_e32 v99, v99
	v_exp_f32_e32 v103, v103
	v_add_f32_e32 v99, 1.0, v99
	v_add_f32_e32 v103, 1.0, v103
	v_rcp_f32_e32 v99, v99
	v_rcp_f32_e32 v103, v103
	v_fma_f32 v99, v99, s51, 0.5
	v_fma_f32 v103, v103, s51, 0.5
	v_cvt_u32_f32_e32 v99, v99
	v_cvt_u32_f32_e32 v103, v103
	v_min_u32_e32 v99, 0xff, v99
	v_min_u32_e32 v103, 0xff, v103
	v_lshl_or_b32 v99, v103, 8, v99
	v_mul_f32_e32 v103, 0xbfb8aa3b, v84
	v_exp_f32_e32 v103, v103
	s_nop 0
	v_add_f32_e32 v103, 1.0, v103
	v_rcp_f32_e32 v103, v103
	s_nop 0
	v_fma_f32 v103, v103, s51, 0.5
	v_cvt_u32_f32_e32 v103, v103
	v_min_u32_sdwa v103, v103, s58 dst_sel:WORD_1 dst_unused:UNUSED_PAD src0_sel:DWORD src1_sel:DWORD
	s_nop 0
	v_or3_b32 v103, v99, v103, v106
	global_store_dwordx2 v[104:105], v[102:103], off offset:128

; __device__ __forceinline__ float sigmoidf_(float x) { return __builtin_amdgcn_rcpf(1.f + __builtin_amdgcn_exp2f(-x * LOG2E)); }
; #define EPI_ROWS(...) _Pragma("unroll") for (int ai = 0; ai < 2; ++ai) _Pragma("unroll") for (int m = 0; m < 4; ++m) { const int row = row0 + ai * 128 + m * 16; __VA_ARGS__ __builtin_amdgcn_sched_barrier(0); }
; __device__ __forceinline__ float red_fq(float s) { s += __shfl_xor(s, 16); s += __shfl_xor(s, 32); return s; }
;     __device__ __forceinline__ void operator()(AccRef acc, const Unit& u, int wr, int wc, int fr, int fq) const {
;         const int row0 = u.pm * 256 + wr * 64 + fr, cw = wc * 32 + 8 * fq; const int pn = u.pn;
;         EPI_ROWS(
;             const float rs = __builtin_amdgcn_rsqf(ss1[row] * (1.f / 1024.f) + EPS);
;             f32x4 v[2][2];
;             _Pragma("unroll") for (int bj = 0; bj < 2; ++bj) { v[bj][0] = acc[ai][bj][m][0] * rs; v[bj][1] = acc[ai][bj][m][1] * rs; }
;             if (pn < 3) {
;                 _Pragma("unroll") for (int bj = 0; bj < 2; ++bj) *(u32x4*)(ZA + (size_t)row * 768 + pn * 256 + bj * 128 + cw) = pack8(v[bj][0], v[bj][1]);
;                 float s = dot8(v[0][0], v[0][1]); if (pn != 1) s += dot8(v[1][0], v[1][1]);
;                 s = red_fq(s); if (fq == 0) unsafeAtomicAdd((pn == 2 ? sskv : ssq) + row, s);
;             } else if (pn < 7) {
;                 _Pragma("unroll") for (int bj = 0; bj < 2; ++bj) *(u32x4*)(ZRX + (size_t)row * 1024 + (pn - 3) * 256 + bj * 128 + cw) = pack8(v[bj][0], v[bj][1]);
;             } else if (pn < 11) {
;                 _Pragma("unroll") for (int bj = 0; bj < 2; ++bj) { _Pragma("unroll") for (int n = 0; n < 2; ++n) _Pragma("unroll") for (int i = 0; i < 4; ++i) v[bj][n][i] = gelu_tanh(v[bj][n][i]);
;                     *(u32x4*)(ZRG + (size_t)row * 1024 + (pn - 7) * 256 + bj * 128 + cw) = pack8(v[bj][0], v[bj][1]); }
;             } else {
;                 _Pragma("unroll") for (int bj = 0; bj < 2; ++bj) { unsigned w[2];
;                     _Pragma("unroll") for (int n = 0; n < 2; ++n) { unsigned q = 0; _Pragma("unroll") for (int i = 0; i < 4; ++i) { const unsigned b = (unsigned)(sigmoidf_(v[bj][n][i]) * 255.f + 0.5f); q |= (b > 255u ? 255u : b) << (8 * i); } w[n] = q; }
;                     *(u32x2*)(ZG8 + (size_t)row * 2048 + (pn - 11) * 256 + bj * 128 + cw) = (u32x2){w[0], w[1]}; }
.LBB0_486:
	s_nop 0
	s_and_b64 vcc, exec, s[10:11]
	s_mov_b64 s[16:17], -1
	s_waitcnt vmcnt(10)
	v_fmamk_f32 v82, v203, 0x3a800000, v155
	v_rsq_f32_e32 v84, v82
	v_or_b32_e32 v82, 48, v140
	s_waitcnt lgkmcnt(0)
	v_ashrrev_i32_e32 v83, 31, v82
	v_pk_mul_f32 v[80:81], v[80:81], v[84:85] op_sel_hi:[1,0]
	v_pk_mul_f32 v[78:79], v[78:79], v[84:85] op_sel_hi:[1,0]
	v_pk_mul_f32 v[76:77], v[76:77], v[84:85] op_sel_hi:[1,0]
	v_pk_mul_f32 v[74:75], v[74:75], v[84:85] op_sel_hi:[1,0]
	v_pk_mul_f32 v[72:73], v[72:73], v[84:85] op_sel_hi:[1,0]
	v_pk_mul_f32 v[70:71], v[70:71], v[84:85] op_sel_hi:[1,0]
	v_pk_mul_f32 v[68:69], v[68:69], v[84:85] op_sel_hi:[1,0]
	v_pk_mul_f32 v[66:67], v[66:67], v[84:85] op_sel_hi:[1,0]
	s_cbranch_vccnz .LBB0_496
	v_lshlrev_b64 v[84:85], 11, v[82:83]
	s_and_b64 vcc, exec, s[12:13]
	s_cbranch_vccnz .LBB0_493
	s_andn2_b64 vcc, exec, s[78:79]
	s_cbranch_vccnz .LBB0_490
	v_mul_f32_e32 v83, 0xbfb8aa3b, v78
	v_mul_f32_e32 v86, 0xbfb8aa3b, v79
	v_exp_f32_e32 v83, v83
	v_exp_f32_e32 v86, v86
	v_mul_f32_e32 v87, 0xbfb8aa3b, v81
	v_exp_f32_e32 v87, v87
	v_add_f32_e32 v83, 1.0, v83
	v_add_f32_e32 v86, 1.0, v86
	v_rcp_f32_e32 v83, v83
	v_rcp_f32_e32 v86, v86
	v_add_f32_e32 v87, 1.0, v87
	v_rcp_f32_e32 v87, v87
	v_fma_f32 v83, v83, s51, 0.5
	v_fma_f32 v86, v86, s51, 0.5
	v_cvt_u32_f32_e32 v83, v83
	v_cvt_u32_f32_e32 v86, v86
	v_fma_f32 v87, v87, s51, 0.5
	v_cvt_u32_f32_e32 v87, v87
	v_min_u32_e32 v83, 0xff, v83
	v_min_u32_e32 v86, 0xff, v86
	v_lshl_or_b32 v83, v86, 8, v83
	v_mul_f32_e32 v86, 0xbfb8aa3b, v80
	v_exp_f32_e32 v86, v86
	v_min_u32_sdwa v87, v87, s58 dst_sel:BYTE_3 dst_unused:UNUSED_PAD src0_sel:DWORD src1_sel:DWORD
	v_mul_f32_e32 v88, 0xbfb8aa3b, v77
	v_exp_f32_e32 v88, v88
	v_add_f32_e32 v86, 1.0, v86
	v_rcp_f32_e32 v86, v86
	v_mul_f32_e32 v90, 0xbfb8aa3b, v69
	v_add_f32_e32 v88, 1.0, v88
	v_rcp_f32_e32 v88, v88
	v_fma_f32 v86, v86, s51, 0.5
	v_cvt_u32_f32_e32 v86, v86
	v_exp_f32_e32 v90, v90
	v_fma_f32 v88, v88, s51, 0.5
	v_cvt_u32_f32_e32 v88, v88
	v_min_u32_sdwa v86, v86, s58 dst_sel:WORD_1 dst_unused:UNUSED_PAD src0_sel:DWORD src1_sel:DWORD
	v_add_f32_e32 v90, 1.0, v90
	v_or3_b32 v86, v83, v86, v87
	v_mul_f32_e32 v83, 0xbfb8aa3b, v74
	v_mul_f32_e32 v87, 0xbfb8aa3b, v75
	v_exp_f32_e32 v83, v83
	v_exp_f32_e32 v87, v87
	v_min_u32_sdwa v88, v88, s58 dst_sel:BYTE_3 dst_unused:UNUSED_PAD src0_sel:DWORD src1_sel:DWORD
	v_rcp_f32_e32 v90, v90
	v_add_f32_e32 v83, 1.0, v83
	v_add_f32_e32 v87, 1.0, v87
	v_rcp_f32_e32 v83, v83
	v_rcp_f32_e32 v87, v87
	v_fma_f32 v90, v90, s51, 0.5
	v_cvt_u32_f32_e32 v90, v90
	v_fma_f32 v83, v83, s51, 0.5
	v_fma_f32 v87, v87, s51, 0.5
	v_cvt_u32_f32_e32 v83, v83
	v_cvt_u32_f32_e32 v87, v87
	v_min_u32_sdwa v90, v90, s58 dst_sel:BYTE_3 dst_unused:UNUSED_PAD src0_sel:DWORD src1_sel:DWORD
	s_mov_b64 s[16:17], 0
	v_min_u32_e32 v83, 0xff, v83
	v_min_u32_e32 v87, 0xff, v87
	v_lshl_or_b32 v83, v87, 8, v83
	v_mul_f32_e32 v87, 0xbfb8aa3b, v76
	v_exp_f32_e32 v87, v87
	s_nop 0
	v_add_f32_e32 v87, 1.0, v87
	v_rcp_f32_e32 v87, v87
	s_nop 0
	v_fma_f32 v87, v87, s51, 0.5
	v_cvt_u32_f32_e32 v87, v87
	v_min_u32_sdwa v87, v87, s58 dst_sel:WORD_1 dst_unused:UNUSED_PAD src0_sel:DWORD src1_sel:DWORD
	s_nop 0
	v_or3_b32 v87, v83, v87, v88
	v_lshl_add_u64 v[88:89], s[22:23], 0, v[84:85]
	v_lshl_add_u64 v[88:89], v[88:89], 0, s[0:1]
	v_lshl_add_u64 v[88:89], v[88:89], 0, v[130:131]
	global_store_dwordx2 v[88:89], v[86:87], off
	v_mul_f32_e32 v83, 0xbfb8aa3b, v70
	v_mul_f32_e32 v86, 0xbfb8aa3b, v71
	v_exp_f32_e32 v83, v83
	v_exp_f32_e32 v86, v86
	v_mul_f32_e32 v87, 0xbfb8aa3b, v73
	v_exp_f32_e32 v87, v87
	v_add_f32_e32 v83, 1.0, v83
	v_add_f32_e32 v86, 1.0, v86
	v_rcp_f32_e32 v83, v83
	v_rcp_f32_e32 v86, v86
	v_add_f32_e32 v87, 1.0, v87
	v_rcp_f32_e32 v87, v87
	v_fma_f32 v83, v83, s51, 0.5
	v_fma_f32 v86, v86, s51, 0.5
	v_cvt_u32_f32_e32 v83, v83
	v_cvt_u32_f32_e32 v86, v86
	v_fma_f32 v87, v87, s51, 0.5
	v_cvt_u32_f32_e32 v87, v87
	v_min_u32_e32 v83, 0xff, v83
	v_min_u32_e32 v86, 0xff, v86
	v_lshl_or_b32 v83, v86, 8, v83
	v_mul_f32_e32 v86, 0xbfb8aa3b, v72
	v_exp_f32_e32 v86, v86
	v_min_u32_sdwa v87, v87, s58 dst_sel:BYTE_3 dst_unused:UNUSED_PAD src0_sel:DWORD src1_sel:DWORD
	v_add_f32_e32 v86, 1.0, v86
	v_rcp_f32_e32 v86, v86
	s_nop 0
	v_fma_f32 v86, v86, s51, 0.5
	v_cvt_u32_f32_e32 v86, v86
	v_min_u32_sdwa v86, v86, s58 dst_sel:WORD_1 dst_unused:UNUSED_PAD src0_sel:DWORD src1_sel:DWORD
	s_nop 0
	v_or3_b32 v86, v83, v86, v87
	v_mul_f32_e32 v83, 0xbfb8aa3b, v66
	v_mul_f32_e32 v87, 0xbfb8aa3b, v67
	v_exp_f32_e32 v83, v83
	v_exp_f32_e32 v87, v87
	v_add_f32_e32 v83, 1.0, v83
	v_add_f32_e32 v87, 1.0, v87
	v_rcp_f32_e32 v83, v83
	v_rcp_f32_e32 v87, v87
	v_fma_f32 v83, v83, s51, 0.5
	v_fma_f32 v87, v87, s51, 0.5
	v_cvt_u32_f32_e32 v83, v83
	v_cvt_u32_f32_e32 v87, v87
	v_min_u32_e32 v83, 0xff, v83
	v_min_u32_e32 v87, 0xff, v87
	v_lshl_or_b32 v83, v87, 8, v83
	v_mul_f32_e32 v87, 0xbfb8aa3b, v68
	v_exp_f32_e32 v87, v87
	s_nop 0
	v_add_f32_e32 v87, 1.0, v87
	v_rcp_f32_e32 v87, v87
	s_nop 0
	v_fma_f32 v87, v87, s51, 0.5
	v_cvt_u32_f32_e32 v87, v87
	v_min_u32_sdwa v87, v87, s58 dst_sel:WORD_1 dst_unused:UNUSED_PAD src0_sel:DWORD src1_sel:DWORD
	s_nop 0
	v_or3_b32 v87, v83, v87, v90
	global_store_dwordx2 v[88:89], v[86:87], off offset:128

; __device__ __forceinline__ float sigmoidf_(float x) { return __builtin_amdgcn_rcpf(1.f + __builtin_amdgcn_exp2f(-x * LOG2E)); }
; #define EPI_ROWS(...) _Pragma("unroll") for (int ai = 0; ai < 2; ++ai) _Pragma("unroll") for (int m = 0; m < 4; ++m) { const int row = row0 + ai * 128 + m * 16; __VA_ARGS__ __builtin_amdgcn_sched_barrier(0); }
; __device__ __forceinline__ float red_fq(float s) { s += __shfl_xor(s, 16); s += __shfl_xor(s, 32); return s; }
;     __device__ __forceinline__ void operator()(AccRef acc, const Unit& u, int wr, int wc, int fr, int fq) const {
;         const int row0 = u.pm * 256 + wr * 64 + fr, cw = wc * 32 + 8 * fq; const int pn = u.pn;
;         EPI_ROWS(
;             const float rs = __builtin_amdgcn_rsqf(ss1[row] * (1.f / 1024.f) + EPS);
;             f32x4 v[2][2];
;             _Pragma("unroll") for (int bj = 0; bj < 2; ++bj) { v[bj][0] = acc[ai][bj][m][0] * rs; v[bj][1] = acc[ai][bj][m][1] * rs; }
;             if (pn < 3) {
;                 _Pragma("unroll") for (int bj = 0; bj < 2; ++bj) *(u32x4*)(ZA + (size_t)row * 768 + pn * 256 + bj * 128 + cw) = pack8(v[bj][0], v[bj][1]);
;                 float s = dot8(v[0][0], v[0][1]); if (pn != 1) s += dot8(v[1][0], v[1][1]);
;                 s = red_fq(s); if (fq == 0) unsafeAtomicAdd((pn == 2 ? sskv : ssq) + row, s);
;             } else if (pn < 7) {
;                 _Pragma("unroll") for (int bj = 0; bj < 2; ++bj) *(u32x4*)(ZRX + (size_t)row * 1024 + (pn - 3) * 256 + bj * 128 + cw) = pack8(v[bj][0], v[bj][1]);
;             } else if (pn < 11) {
;                 _Pragma("unroll") for (int bj = 0; bj < 2; ++bj) { _Pragma("unroll") for (int n = 0; n < 2; ++n) _Pragma("unroll") for (int i = 0; i < 4; ++i) v[bj][n][i] = gelu_tanh(v[bj][n][i]);
;                     *(u32x4*)(ZRG + (size_t)row * 1024 + (pn - 7) * 256 + bj * 128 + cw) = pack8(v[bj][0], v[bj][1]); }
;             } else {
;                 _Pragma("unroll") for (int bj = 0; bj < 2; ++bj) { unsigned w[2];
;                     _Pragma("unroll") for (int n = 0; n < 2; ++n) { unsigned q = 0; _Pragma("unroll") for (int i = 0; i < 4; ++i) { const unsigned b = (unsigned)(sigmoidf_(v[bj][n][i]) * 255.f + 0.5f); q |= (b > 255u ? 255u : b) << (8 * i); } w[n] = q; }
;                     *(u32x2*)(ZG8 + (size_t)row * 2048 + (pn - 11) * 256 + bj * 128 + cw) = (u32x2){w[0], w[1]}; }
.LBB0_502:
	s_nop 0
	s_and_b64 vcc, exec, s[10:11]
	s_mov_b64 s[16:17], -1
	s_waitcnt vmcnt(11)
	v_fmamk_f32 v66, v204, 0x3a800000, v155
	v_rsq_f32_e32 v68, v66
	v_add_u32_e32 v66, 0x80, v140
	s_waitcnt lgkmcnt(0)
	v_ashrrev_i32_e32 v67, 31, v66
	v_pk_mul_f32 v[64:65], v[64:65], v[68:69] op_sel_hi:[1,0]
	v_pk_mul_f32 v[62:63], v[62:63], v[68:69] op_sel_hi:[1,0]
	v_pk_mul_f32 v[60:61], v[60:61], v[68:69] op_sel_hi:[1,0]
	v_pk_mul_f32 v[58:59], v[58:59], v[68:69] op_sel_hi:[1,0]
	v_pk_mul_f32 v[56:57], v[56:57], v[68:69] op_sel_hi:[1,0]
	v_pk_mul_f32 v[54:55], v[54:55], v[68:69] op_sel_hi:[1,0]
	v_pk_mul_f32 v[52:53], v[52:53], v[68:69] op_sel_hi:[1,0]
	v_pk_mul_f32 v[50:51], v[50:51], v[68:69] op_sel_hi:[1,0]
	s_cbranch_vccnz .LBB0_512
	v_lshlrev_b64 v[68:69], 11, v[66:67]
	s_and_b64 vcc, exec, s[12:13]
	s_cbranch_vccnz .LBB0_509
	s_andn2_b64 vcc, exec, s[78:79]
	s_cbranch_vccnz .LBB0_506
	v_mul_f32_e32 v67, 0xbfb8aa3b, v62
	v_mul_f32_e32 v70, 0xbfb8aa3b, v63
	v_exp_f32_e32 v67, v67
	v_exp_f32_e32 v70, v70
	v_mul_f32_e32 v71, 0xbfb8aa3b, v65
	v_exp_f32_e32 v71, v71
	v_add_f32_e32 v67, 1.0, v67
	v_add_f32_e32 v70, 1.0, v70
	v_rcp_f32_e32 v67, v67
	v_rcp_f32_e32 v70, v70
	v_add_f32_e32 v71, 1.0, v71
	v_rcp_f32_e32 v71, v71
	v_fma_f32 v67, v67, s51, 0.5
	v_fma_f32 v70, v70, s51, 0.5
	v_cvt_u32_f32_e32 v67, v67
	v_cvt_u32_f32_e32 v70, v70
	v_fma_f32 v71, v71, s51, 0.5
	v_cvt_u32_f32_e32 v71, v71
	v_min_u32_e32 v67, 0xff, v67
	v_min_u32_e32 v70, 0xff, v70
	v_lshl_or_b32 v67, v70, 8, v67
	v_mul_f32_e32 v70, 0xbfb8aa3b, v64
	v_exp_f32_e32 v70, v70
	v_min_u32_sdwa v71, v71, s58 dst_sel:BYTE_3 dst_unused:UNUSED_PAD src0_sel:DWORD src1_sel:DWORD
	v_mul_f32_e32 v72, 0xbfb8aa3b, v61
	v_exp_f32_e32 v72, v72
	v_add_f32_e32 v70, 1.0, v70
	v_rcp_f32_e32 v70, v70
	v_mul_f32_e32 v74, 0xbfb8aa3b, v53
	v_add_f32_e32 v72, 1.0, v72
	v_rcp_f32_e32 v72, v72
	v_fma_f32 v70, v70, s51, 0.5
	v_cvt_u32_f32_e32 v70, v70
	v_exp_f32_e32 v74, v74
	v_fma_f32 v72, v72, s51, 0.5
	v_cvt_u32_f32_e32 v72, v72
	v_min_u32_sdwa v70, v70, s58 dst_sel:WORD_1 dst_unused:UNUSED_PAD src0_sel:DWORD src1_sel:DWORD
	v_add_f32_e32 v74, 1.0, v74
	v_or3_b32 v70, v67, v70, v71
	v_mul_f32_e32 v67, 0xbfb8aa3b, v58
	v_mul_f32_e32 v71, 0xbfb8aa3b, v59
	v_exp_f32_e32 v67, v67
	v_exp_f32_e32 v71, v71
	v_min_u32_sdwa v72, v72, s58 dst_sel:BYTE_3 dst_unused:UNUSED_PAD src0_sel:DWORD src1_sel:DWORD
	v_rcp_f32_e32 v74, v74
	v_add_f32_e32 v67, 1.0, v67
	v_add_f32_e32 v71, 1.0, v71
	v_rcp_f32_e32 v67, v67
	v_rcp_f32_e32 v71, v71
	v_fma_f32 v74, v74, s51, 0.5
	v_cvt_u32_f32_e32 v74, v74
	v_fma_f32 v67, v67, s51, 0.5
	v_fma_f32 v71, v71, s51, 0.5
	v_cvt_u32_f32_e32 v67, v67
	v_cvt_u32_f32_e32 v71, v71
	v_min_u32_sdwa v74, v74, s58 dst_sel:BYTE_3 dst_unused:UNUSED_PAD src0_sel:DWORD src1_sel:DWORD
	s_mov_b64 s[16:17], 0
	v_min_u32_e32 v67, 0xff, v67
	v_min_u32_e32 v71, 0xff, v71
	v_lshl_or_b32 v67, v71, 8, v67
	v_mul_f32_e32 v71, 0xbfb8aa3b, v60
	v_exp_f32_e32 v71, v71
	s_nop 0
	v_add_f32_e32 v71, 1.0, v71
	v_rcp_f32_e32 v71, v71
	s_nop 0
	v_fma_f32 v71, v71, s51, 0.5
	v_cvt_u32_f32_e32 v71, v71
	v_min_u32_sdwa v71, v71, s58 dst_sel:WORD_1 dst_unused:UNUSED_PAD src0_sel:DWORD src1_sel:DWORD
	s_nop 0
	v_or3_b32 v71, v67, v71, v72
	v_lshl_add_u64 v[72:73], s[22:23], 0, v[68:69]
	v_lshl_add_u64 v[72:73], v[72:73], 0, s[0:1]
	v_lshl_add_u64 v[72:73], v[72:73], 0, v[130:131]
	global_store_dwordx2 v[72:73], v[70:71], off
	v_mul_f32_e32 v67, 0xbfb8aa3b, v54
	v_mul_f32_e32 v70, 0xbfb8aa3b, v55
	v_exp_f32_e32 v67, v67
	v_exp_f32_e32 v70, v70
	v_mul_f32_e32 v71, 0xbfb8aa3b, v57
	v_exp_f32_e32 v71, v71
	v_add_f32_e32 v67, 1.0, v67
	v_add_f32_e32 v70, 1.0, v70
	v_rcp_f32_e32 v67, v67
	v_rcp_f32_e32 v70, v70
	v_add_f32_e32 v71, 1.0, v71
	v_rcp_f32_e32 v71, v71
	v_fma_f32 v67, v67, s51, 0.5
	v_fma_f32 v70, v70, s51, 0.5
	v_cvt_u32_f32_e32 v67, v67
	v_cvt_u32_f32_e32 v70, v70
	v_fma_f32 v71, v71, s51, 0.5
	v_cvt_u32_f32_e32 v71, v71
	v_min_u32_e32 v67, 0xff, v67
	v_min_u32_e32 v70, 0xff, v70
	v_lshl_or_b32 v67, v70, 8, v67
	v_mul_f32_e32 v70, 0xbfb8aa3b, v56
	v_exp_f32_e32 v70, v70
	v_min_u32_sdwa v71, v71, s58 dst_sel:BYTE_3 dst_unused:UNUSED_PAD src0_sel:DWORD src1_sel:DWORD
	v_add_f32_e32 v70, 1.0, v70
	v_rcp_f32_e32 v70, v70
	s_nop 0
	v_fma_f32 v70, v70, s51, 0.5
	v_cvt_u32_f32_e32 v70, v70
	v_min_u32_sdwa v70, v70, s58 dst_sel:WORD_1 dst_unused:UNUSED_PAD src0_sel:DWORD src1_sel:DWORD
	s_nop 0
	v_or3_b32 v70, v67, v70, v71
	v_mul_f32_e32 v67, 0xbfb8aa3b, v50
	v_mul_f32_e32 v71, 0xbfb8aa3b, v51
	v_exp_f32_e32 v67, v67
	v_exp_f32_e32 v71, v71
	v_add_f32_e32 v67, 1.0, v67
	v_add_f32_e32 v71, 1.0, v71
	v_rcp_f32_e32 v67, v67
	v_rcp_f32_e32 v71, v71
	v_fma_f32 v67, v67, s51, 0.5
	v_fma_f32 v71, v71, s51, 0.5
	v_cvt_u32_f32_e32 v67, v67
	v_cvt_u32_f32_e32 v71, v71
	v_min_u32_e32 v67, 0xff, v67
	v_min_u32_e32 v71, 0xff, v71
	v_lshl_or_b32 v67, v71, 8, v67
	v_mul_f32_e32 v71, 0xbfb8aa3b, v52
	v_exp_f32_e32 v71, v71
	s_nop 0
	v_add_f32_e32 v71, 1.0, v71
	v_rcp_f32_e32 v71, v71
	s_nop 0
	v_fma_f32 v71, v71, s51, 0.5
	v_cvt_u32_f32_e32 v71, v71
	v_min_u32_sdwa v71, v71, s58 dst_sel:WORD_1 dst_unused:UNUSED_PAD src0_sel:DWORD src1_sel:DWORD
	s_nop 0
	v_or3_b32 v71, v67, v71, v74
	global_store_dwordx2 v[72:73], v[70:71], off offset:128

; __device__ __forceinline__ float sigmoidf_(float x) { return __builtin_amdgcn_rcpf(1.f + __builtin_amdgcn_exp2f(-x * LOG2E)); }
; #define EPI_ROWS(...) _Pragma("unroll") for (int ai = 0; ai < 2; ++ai) _Pragma("unroll") for (int m = 0; m < 4; ++m) { const int row = row0 + ai * 128 + m * 16; __VA_ARGS__ __builtin_amdgcn_sched_barrier(0); }
; __device__ __forceinline__ float red_fq(float s) { s += __shfl_xor(s, 16); s += __shfl_xor(s, 32); return s; }
;     __device__ __forceinline__ void operator()(AccRef acc, const Unit& u, int wr, int wc, int fr, int fq) const {
;         const int row0 = u.pm * 256 + wr * 64 + fr, cw = wc * 32 + 8 * fq; const int pn = u.pn;
;         EPI_ROWS(
;             const float rs = __builtin_amdgcn_rsqf(ss1[row] * (1.f / 1024.f) + EPS);
;             f32x4 v[2][2];
;             _Pragma("unroll") for (int bj = 0; bj < 2; ++bj) { v[bj][0] = acc[ai][bj][m][0] * rs; v[bj][1] = acc[ai][bj][m][1] * rs; }
;             if (pn < 3) {
;                 _Pragma("unroll") for (int bj = 0; bj < 2; ++bj) *(u32x4*)(ZA + (size_t)row * 768 + pn * 256 + bj * 128 + cw) = pack8(v[bj][0], v[bj][1]);
;                 float s = dot8(v[0][0], v[0][1]); if (pn != 1) s += dot8(v[1][0], v[1][1]);
;                 s = red_fq(s); if (fq == 0) unsafeAtomicAdd((pn == 2 ? sskv : ssq) + row, s);
;             } else if (pn < 7) {
;                 _Pragma("unroll") for (int bj = 0; bj < 2; ++bj) *(u32x4*)(ZRX + (size_t)row * 1024 + (pn - 3) * 256 + bj * 128 + cw) = pack8(v[bj][0], v[bj][1]);
;             } else if (pn < 11) {
;                 _Pragma("unroll") for (int bj = 0; bj < 2; ++bj) { _Pragma("unroll") for (int n = 0; n < 2; ++n) _Pragma("unroll") for (int i = 0; i < 4; ++i) v[bj][n][i] = gelu_tanh(v[bj][n][i]);
;                     *(u32x4*)(ZRG + (size_t)row * 1024 + (pn - 7) * 256 + bj * 128 + cw) = pack8(v[bj][0], v[bj][1]); }
;             } else {
;                 _Pragma("unroll") for (int bj = 0; bj < 2; ++bj) { unsigned w[2];
;                     _Pragma("unroll") for (int n = 0; n < 2; ++n) { unsigned q = 0; _Pragma("unroll") for (int i = 0; i < 4; ++i) { const unsigned b = (unsigned)(sigmoidf_(v[bj][n][i]) * 255.f + 0.5f); q |= (b > 255u ? 255u : b) << (8 * i); } w[n] = q; }
;                     *(u32x2*)(ZG8 + (size_t)row * 2048 + (pn - 11) * 256 + bj * 128 + cw) = (u32x2){w[0], w[1]}; }
.LBB0_518:
	s_nop 0
	s_and_b64 vcc, exec, s[10:11]
	s_mov_b64 s[16:17], -1
	s_waitcnt vmcnt(12)
	v_fmamk_f32 v50, v205, 0x3a800000, v155
	v_rsq_f32_e32 v52, v50
	v_add_u32_e32 v50, 0x90, v140
	s_waitcnt lgkmcnt(0)
	v_ashrrev_i32_e32 v51, 31, v50
	v_pk_mul_f32 v[48:49], v[48:49], v[52:53] op_sel_hi:[1,0]
	v_pk_mul_f32 v[46:47], v[46:47], v[52:53] op_sel_hi:[1,0]
	v_pk_mul_f32 v[44:45], v[44:45], v[52:53] op_sel_hi:[1,0]
	v_pk_mul_f32 v[42:43], v[42:43], v[52:53] op_sel_hi:[1,0]
	v_pk_mul_f32 v[40:41], v[40:41], v[52:53] op_sel_hi:[1,0]
	v_pk_mul_f32 v[38:39], v[38:39], v[52:53] op_sel_hi:[1,0]
	v_pk_mul_f32 v[36:37], v[36:37], v[52:53] op_sel_hi:[1,0]
	v_pk_mul_f32 v[34:35], v[34:35], v[52:53] op_sel_hi:[1,0]
	s_cbranch_vccnz .LBB0_528
	v_lshlrev_b64 v[52:53], 11, v[50:51]
	s_and_b64 vcc, exec, s[12:13]
	s_cbranch_vccnz .LBB0_525
	s_andn2_b64 vcc, exec, s[78:79]
	s_cbranch_vccnz .LBB0_522
	v_mul_f32_e32 v51, 0xbfb8aa3b, v46
	v_mul_f32_e32 v54, 0xbfb8aa3b, v47
	v_exp_f32_e32 v51, v51
	v_exp_f32_e32 v54, v54
	v_mul_f32_e32 v55, 0xbfb8aa3b, v49
	v_exp_f32_e32 v55, v55
	v_add_f32_e32 v51, 1.0, v51
	v_add_f32_e32 v54, 1.0, v54
	v_rcp_f32_e32 v51, v51
	v_rcp_f32_e32 v54, v54
	v_add_f32_e32 v55, 1.0, v55
	v_rcp_f32_e32 v55, v55
	v_fma_f32 v51, v51, s51, 0.5
	v_fma_f32 v54, v54, s51, 0.5
	v_cvt_u32_f32_e32 v51, v51
	v_cvt_u32_f32_e32 v54, v54
	v_fma_f32 v55, v55, s51, 0.5
	v_cvt_u32_f32_e32 v55, v55
	v_min_u32_e32 v51, 0xff, v51
	v_min_u32_e32 v54, 0xff, v54
	v_lshl_or_b32 v51, v54, 8, v51
	v_mul_f32_e32 v54, 0xbfb8aa3b, v48
	v_exp_f32_e32 v54, v54
	v_min_u32_sdwa v55, v55, s58 dst_sel:BYTE_3 dst_unused:UNUSED_PAD src0_sel:DWORD src1_sel:DWORD
	v_mul_f32_e32 v56, 0xbfb8aa3b, v45
	v_exp_f32_e32 v56, v56
	v_add_f32_e32 v54, 1.0, v54
	v_rcp_f32_e32 v54, v54
	v_mul_f32_e32 v58, 0xbfb8aa3b, v37
	v_add_f32_e32 v56, 1.0, v56
	v_rcp_f32_e32 v56, v56
	v_fma_f32 v54, v54, s51, 0.5
	v_cvt_u32_f32_e32 v54, v54
	v_exp_f32_e32 v58, v58
	v_fma_f32 v56, v56, s51, 0.5
	v_cvt_u32_f32_e32 v56, v56
	v_min_u32_sdwa v54, v54, s58 dst_sel:WORD_1 dst_unused:UNUSED_PAD src0_sel:DWORD src1_sel:DWORD
	v_add_f32_e32 v58, 1.0, v58
	v_or3_b32 v54, v51, v54, v55
	v_mul_f32_e32 v51, 0xbfb8aa3b, v42
	v_mul_f32_e32 v55, 0xbfb8aa3b, v43
	v_exp_f32_e32 v51, v51
	v_exp_f32_e32 v55, v55
	v_min_u32_sdwa v56, v56, s58 dst_sel:BYTE_3 dst_unused:UNUSED_PAD src0_sel:DWORD src1_sel:DWORD
	v_rcp_f32_e32 v58, v58
	v_add_f32_e32 v51, 1.0, v51
	v_add_f32_e32 v55, 1.0, v55
	v_rcp_f32_e32 v51, v51
	v_rcp_f32_e32 v55, v55
	v_fma_f32 v58, v58, s51, 0.5
	v_cvt_u32_f32_e32 v58, v58
	v_fma_f32 v51, v51, s51, 0.5
	v_fma_f32 v55, v55, s51, 0.5
	v_cvt_u32_f32_e32 v51, v51
	v_cvt_u32_f32_e32 v55, v55
	v_min_u32_sdwa v58, v58, s58 dst_sel:BYTE_3 dst_unused:UNUSED_PAD src0_sel:DWORD src1_sel:DWORD
	s_mov_b64 s[16:17], 0
	v_min_u32_e32 v51, 0xff, v51
	v_min_u32_e32 v55, 0xff, v55
	v_lshl_or_b32 v51, v55, 8, v51
	v_mul_f32_e32 v55, 0xbfb8aa3b, v44
	v_exp_f32_e32 v55, v55
	s_nop 0
	v_add_f32_e32 v55, 1.0, v55
	v_rcp_f32_e32 v55, v55
	s_nop 0
	v_fma_f32 v55, v55, s51, 0.5
	v_cvt_u32_f32_e32 v55, v55
	v_min_u32_sdwa v55, v55, s58 dst_sel:WORD_1 dst_unused:UNUSED_PAD src0_sel:DWORD src1_sel:DWORD
	s_nop 0
	v_or3_b32 v55, v51, v55, v56
	v_lshl_add_u64 v[56:57], s[22:23], 0, v[52:53]
	v_lshl_add_u64 v[56:57], v[56:57], 0, s[0:1]
	v_lshl_add_u64 v[56:57], v[56:57], 0, v[130:131]
	global_store_dwordx2 v[56:57], v[54:55], off
	v_mul_f32_e32 v51, 0xbfb8aa3b, v38
	v_mul_f32_e32 v54, 0xbfb8aa3b, v39
	v_exp_f32_e32 v51, v51
	v_exp_f32_e32 v54, v54
	v_mul_f32_e32 v55, 0xbfb8aa3b, v41
	v_exp_f32_e32 v55, v55
	v_add_f32_e32 v51, 1.0, v51
	v_add_f32_e32 v54, 1.0, v54
	v_rcp_f32_e32 v51, v51
	v_rcp_f32_e32 v54, v54
	v_add_f32_e32 v55, 1.0, v55
	v_rcp_f32_e32 v55, v55
	v_fma_f32 v51, v51, s51, 0.5
	v_fma_f32 v54, v54, s51, 0.5
	v_cvt_u32_f32_e32 v51, v51
	v_cvt_u32_f32_e32 v54, v54
	v_fma_f32 v55, v55, s51, 0.5
	v_cvt_u32_f32_e32 v55, v55
	v_min_u32_e32 v51, 0xff, v51
	v_min_u32_e32 v54, 0xff, v54
	v_lshl_or_b32 v51, v54, 8, v51
	v_mul_f32_e32 v54, 0xbfb8aa3b, v40
	v_exp_f32_e32 v54, v54
	v_min_u32_sdwa v55, v55, s58 dst_sel:BYTE_3 dst_unused:UNUSED_PAD src0_sel:DWORD src1_sel:DWORD
	v_add_f32_e32 v54, 1.0, v54
	v_rcp_f32_e32 v54, v54
	s_nop 0
	v_fma_f32 v54, v54, s51, 0.5
	v_cvt_u32_f32_e32 v54, v54
	v_min_u32_sdwa v54, v54, s58 dst_sel:WORD_1 dst_unused:UNUSED_PAD src0_sel:DWORD src1_sel:DWORD
	s_nop 0
	v_or3_b32 v54, v51, v54, v55
	v_mul_f32_e32 v51, 0xbfb8aa3b, v34
	v_mul_f32_e32 v55, 0xbfb8aa3b, v35
	v_exp_f32_e32 v51, v51
	v_exp_f32_e32 v55, v55
	v_add_f32_e32 v51, 1.0, v51
	v_add_f32_e32 v55, 1.0, v55
	v_rcp_f32_e32 v51, v51
	v_rcp_f32_e32 v55, v55
	v_fma_f32 v51, v51, s51, 0.5
	v_fma_f32 v55, v55, s51, 0.5
	v_cvt_u32_f32_e32 v51, v51
	v_cvt_u32_f32_e32 v55, v55
	v_min_u32_e32 v51, 0xff, v51
	v_min_u32_e32 v55, 0xff, v55
	v_lshl_or_b32 v51, v55, 8, v51
	v_mul_f32_e32 v55, 0xbfb8aa3b, v36
	v_exp_f32_e32 v55, v55
	s_nop 0
	v_add_f32_e32 v55, 1.0, v55
	v_rcp_f32_e32 v55, v55
	s_nop 0
	v_fma_f32 v55, v55, s51, 0.5
	v_cvt_u32_f32_e32 v55, v55
	v_min_u32_sdwa v55, v55, s58 dst_sel:WORD_1 dst_unused:UNUSED_PAD src0_sel:DWORD src1_sel:DWORD
	s_nop 0
	v_or3_b32 v55, v51, v55, v58
	global_store_dwordx2 v[56:57], v[54:55], off offset:128

; __device__ __forceinline__ float sigmoidf_(float x) { return __builtin_amdgcn_rcpf(1.f + __builtin_amdgcn_exp2f(-x * LOG2E)); }
; #define EPI_ROWS(...) _Pragma("unroll") for (int ai = 0; ai < 2; ++ai) _Pragma("unroll") for (int m = 0; m < 4; ++m) { const int row = row0 + ai * 128 + m * 16; __VA_ARGS__ __builtin_amdgcn_sched_barrier(0); }
; __device__ __forceinline__ float red_fq(float s) { s += __shfl_xor(s, 16); s += __shfl_xor(s, 32); return s; }
;     __device__ __forceinline__ void operator()(AccRef acc, const Unit& u, int wr, int wc, int fr, int fq) const {
;         const int row0 = u.pm * 256 + wr * 64 + fr, cw = wc * 32 + 8 * fq; const int pn = u.pn;
;         EPI_ROWS(
;             const float rs = __builtin_amdgcn_rsqf(ss1[row] * (1.f / 1024.f) + EPS);
;             f32x4 v[2][2];
;             _Pragma("unroll") for (int bj = 0; bj < 2; ++bj) { v[bj][0] = acc[ai][bj][m][0] * rs; v[bj][1] = acc[ai][bj][m][1] * rs; }
;             if (pn < 3) {
;                 _Pragma("unroll") for (int bj = 0; bj < 2; ++bj) *(u32x4*)(ZA + (size_t)row * 768 + pn * 256 + bj * 128 + cw) = pack8(v[bj][0], v[bj][1]);
;                 float s = dot8(v[0][0], v[0][1]); if (pn != 1) s += dot8(v[1][0], v[1][1]);
;                 s = red_fq(s); if (fq == 0) unsafeAtomicAdd((pn == 2 ? sskv : ssq) + row, s);
;             } else if (pn < 7) {
;                 _Pragma("unroll") for (int bj = 0; bj < 2; ++bj) *(u32x4*)(ZRX + (size_t)row * 1024 + (pn - 3) * 256 + bj * 128 + cw) = pack8(v[bj][0], v[bj][1]);
;             } else if (pn < 11) {
;                 _Pragma("unroll") for (int bj = 0; bj < 2; ++bj) { _Pragma("unroll") for (int n = 0; n < 2; ++n) _Pragma("unroll") for (int i = 0; i < 4; ++i) v[bj][n][i] = gelu_tanh(v[bj][n][i]);
;                     *(u32x4*)(ZRG + (size_t)row * 1024 + (pn - 7) * 256 + bj * 128 + cw) = pack8(v[bj][0], v[bj][1]); }
;             } else {
;                 _Pragma("unroll") for (int bj = 0; bj < 2; ++bj) { unsigned w[2];
;                     _Pragma("unroll") for (int n = 0; n < 2; ++n) { unsigned q = 0; _Pragma("unroll") for (int i = 0; i < 4; ++i) { const unsigned b = (unsigned)(sigmoidf_(v[bj][n][i]) * 255.f + 0.5f); q |= (b > 255u ? 255u : b) << (8 * i); } w[n] = q; }
;                     *(u32x2*)(ZG8 + (size_t)row * 2048 + (pn - 11) * 256 + bj * 128 + cw) = (u32x2){w[0], w[1]}; }
.LBB0_534:
	s_nop 0
	s_and_b64 vcc, exec, s[10:11]
	s_mov_b64 s[16:17], -1
	s_waitcnt vmcnt(13)
	v_fmamk_f32 v34, v206, 0x3a800000, v155
	v_rsq_f32_e32 v36, v34
	v_add_u32_e32 v34, 0xa0, v140
	s_waitcnt lgkmcnt(0)
	v_ashrrev_i32_e32 v35, 31, v34
	v_pk_mul_f32 v[32:33], v[32:33], v[36:37] op_sel_hi:[1,0]
	v_pk_mul_f32 v[30:31], v[30:31], v[36:37] op_sel_hi:[1,0]
	v_pk_mul_f32 v[28:29], v[28:29], v[36:37] op_sel_hi:[1,0]
	v_pk_mul_f32 v[26:27], v[26:27], v[36:37] op_sel_hi:[1,0]
	v_pk_mul_f32 v[24:25], v[24:25], v[36:37] op_sel_hi:[1,0]
	v_pk_mul_f32 v[22:23], v[22:23], v[36:37] op_sel_hi:[1,0]
	v_pk_mul_f32 v[20:21], v[20:21], v[36:37] op_sel_hi:[1,0]
	v_pk_mul_f32 v[18:19], v[18:19], v[36:37] op_sel_hi:[1,0]
	s_cbranch_vccnz .LBB0_544
	v_lshlrev_b64 v[36:37], 11, v[34:35]
	s_and_b64 vcc, exec, s[12:13]
	s_cbranch_vccnz .LBB0_541
	s_andn2_b64 vcc, exec, s[78:79]
	s_cbranch_vccnz .LBB0_538
	v_mul_f32_e32 v35, 0xbfb8aa3b, v30
	v_mul_f32_e32 v38, 0xbfb8aa3b, v31
	v_exp_f32_e32 v35, v35
	v_exp_f32_e32 v38, v38
	v_mul_f32_e32 v39, 0xbfb8aa3b, v33
	v_exp_f32_e32 v39, v39
	v_add_f32_e32 v35, 1.0, v35
	v_add_f32_e32 v38, 1.0, v38
	v_rcp_f32_e32 v35, v35
	v_rcp_f32_e32 v38, v38
	v_add_f32_e32 v39, 1.0, v39
	v_rcp_f32_e32 v39, v39
	v_fma_f32 v35, v35, s51, 0.5
	v_fma_f32 v38, v38, s51, 0.5
	v_cvt_u32_f32_e32 v35, v35
	v_cvt_u32_f32_e32 v38, v38
	v_fma_f32 v39, v39, s51, 0.5
	v_cvt_u32_f32_e32 v39, v39
	v_min_u32_e32 v35, 0xff, v35
	v_min_u32_e32 v38, 0xff, v38
	v_lshl_or_b32 v35, v38, 8, v35
	v_mul_f32_e32 v38, 0xbfb8aa3b, v32
	v_exp_f32_e32 v38, v38
	v_min_u32_sdwa v39, v39, s58 dst_sel:BYTE_3 dst_unused:UNUSED_PAD src0_sel:DWORD src1_sel:DWORD
	v_mul_f32_e32 v40, 0xbfb8aa3b, v29
	v_exp_f32_e32 v40, v40
	v_add_f32_e32 v38, 1.0, v38
	v_rcp_f32_e32 v38, v38
	v_mul_f32_e32 v42, 0xbfb8aa3b, v21
	v_add_f32_e32 v40, 1.0, v40
	v_rcp_f32_e32 v40, v40
	v_fma_f32 v38, v38, s51, 0.5
	v_cvt_u32_f32_e32 v38, v38
	v_exp_f32_e32 v42, v42
	v_fma_f32 v40, v40, s51, 0.5
	v_cvt_u32_f32_e32 v40, v40
	v_min_u32_sdwa v38, v38, s58 dst_sel:WORD_1 dst_unused:UNUSED_PAD src0_sel:DWORD src1_sel:DWORD
	v_add_f32_e32 v42, 1.0, v42
	v_or3_b32 v38, v35, v38, v39
	v_mul_f32_e32 v35, 0xbfb8aa3b, v26
	v_mul_f32_e32 v39, 0xbfb8aa3b, v27
	v_exp_f32_e32 v35, v35
	v_exp_f32_e32 v39, v39
	v_min_u32_sdwa v40, v40, s58 dst_sel:BYTE_3 dst_unused:UNUSED_PAD src0_sel:DWORD src1_sel:DWORD
	v_rcp_f32_e32 v42, v42
	v_add_f32_e32 v35, 1.0, v35
	v_add_f32_e32 v39, 1.0, v39
	v_rcp_f32_e32 v35, v35
	v_rcp_f32_e32 v39, v39
	v_fma_f32 v42, v42, s51, 0.5
	v_cvt_u32_f32_e32 v42, v42
	v_fma_f32 v35, v35, s51, 0.5
	v_fma_f32 v39, v39, s51, 0.5
	v_cvt_u32_f32_e32 v35, v35
	v_cvt_u32_f32_e32 v39, v39
	v_min_u32_sdwa v42, v42, s58 dst_sel:BYTE_3 dst_unused:UNUSED_PAD src0_sel:DWORD src1_sel:DWORD
	s_mov_b64 s[16:17], 0
	v_min_u32_e32 v35, 0xff, v35
	v_min_u32_e32 v39, 0xff, v39
	v_lshl_or_b32 v35, v39, 8, v35
	v_mul_f32_e32 v39, 0xbfb8aa3b, v28
	v_exp_f32_e32 v39, v39
	s_nop 0
	v_add_f32_e32 v39, 1.0, v39
	v_rcp_f32_e32 v39, v39
	s_nop 0
	v_fma_f32 v39, v39, s51, 0.5
	v_cvt_u32_f32_e32 v39, v39
	v_min_u32_sdwa v39, v39, s58 dst_sel:WORD_1 dst_unused:UNUSED_PAD src0_sel:DWORD src1_sel:DWORD
	s_nop 0
	v_or3_b32 v39, v35, v39, v40
	v_lshl_add_u64 v[40:41], s[22:23], 0, v[36:37]
	v_lshl_add_u64 v[40:41], v[40:41], 0, s[0:1]
	v_lshl_add_u64 v[40:41], v[40:41], 0, v[130:131]
	global_store_dwordx2 v[40:41], v[38:39], off
	v_mul_f32_e32 v35, 0xbfb8aa3b, v22
	v_mul_f32_e32 v38, 0xbfb8aa3b, v23
	v_exp_f32_e32 v35, v35
	v_exp_f32_e32 v38, v38
	v_mul_f32_e32 v39, 0xbfb8aa3b, v25
	v_exp_f32_e32 v39, v39
	v_add_f32_e32 v35, 1.0, v35
	v_add_f32_e32 v38, 1.0, v38
	v_rcp_f32_e32 v35, v35
	v_rcp_f32_e32 v38, v38
	v_add_f32_e32 v39, 1.0, v39
	v_rcp_f32_e32 v39, v39
	v_fma_f32 v35, v35, s51, 0.5
	v_fma_f32 v38, v38, s51, 0.5
	v_cvt_u32_f32_e32 v35, v35
	v_cvt_u32_f32_e32 v38, v38
	v_fma_f32 v39, v39, s51, 0.5
	v_cvt_u32_f32_e32 v39, v39
	v_min_u32_e32 v35, 0xff, v35
	v_min_u32_e32 v38, 0xff, v38
	v_lshl_or_b32 v35, v38, 8, v35
	v_mul_f32_e32 v38, 0xbfb8aa3b, v24
	v_exp_f32_e32 v38, v38
	v_min_u32_sdwa v39, v39, s58 dst_sel:BYTE_3 dst_unused:UNUSED_PAD src0_sel:DWORD src1_sel:DWORD
	v_add_f32_e32 v38, 1.0, v38
	v_rcp_f32_e32 v38, v38
	s_nop 0
	v_fma_f32 v38, v38, s51, 0.5
	v_cvt_u32_f32_e32 v38, v38
	v_min_u32_sdwa v38, v38, s58 dst_sel:WORD_1 dst_unused:UNUSED_PAD src0_sel:DWORD src1_sel:DWORD
	s_nop 0
	v_or3_b32 v38, v35, v38, v39
	v_mul_f32_e32 v35, 0xbfb8aa3b, v18
	v_mul_f32_e32 v39, 0xbfb8aa3b, v19
	v_exp_f32_e32 v35, v35
	v_exp_f32_e32 v39, v39
	v_add_f32_e32 v35, 1.0, v35
	v_add_f32_e32 v39, 1.0, v39
	v_rcp_f32_e32 v35, v35
	v_rcp_f32_e32 v39, v39
	v_fma_f32 v35, v35, s51, 0.5
	v_fma_f32 v39, v39, s51, 0.5
	v_cvt_u32_f32_e32 v35, v35
	v_cvt_u32_f32_e32 v39, v39
	v_min_u32_e32 v35, 0xff, v35
	v_min_u32_e32 v39, 0xff, v39
	v_lshl_or_b32 v35, v39, 8, v35
	v_mul_f32_e32 v39, 0xbfb8aa3b, v20
	v_exp_f32_e32 v39, v39
	s_nop 0
	v_add_f32_e32 v39, 1.0, v39
	v_rcp_f32_e32 v39, v39
	s_nop 0
	v_fma_f32 v39, v39, s51, 0.5
	v_cvt_u32_f32_e32 v39, v39
	v_min_u32_sdwa v39, v39, s58 dst_sel:WORD_1 dst_unused:UNUSED_PAD src0_sel:DWORD src1_sel:DWORD
	s_nop 0
	v_or3_b32 v39, v35, v39, v42
	global_store_dwordx2 v[40:41], v[38:39], off offset:128

; __device__ __forceinline__ float sigmoidf_(float x) { return __builtin_amdgcn_rcpf(1.f + __builtin_amdgcn_exp2f(-x * LOG2E)); }
; #define EPI_ROWS(...) _Pragma("unroll") for (int ai = 0; ai < 2; ++ai) _Pragma("unroll") for (int m = 0; m < 4; ++m) { const int row = row0 + ai * 128 + m * 16; __VA_ARGS__ __builtin_amdgcn_sched_barrier(0); }
; __device__ __forceinline__ float red_fq(float s) { s += __shfl_xor(s, 16); s += __shfl_xor(s, 32); return s; }
;     __device__ __forceinline__ void operator()(AccRef acc, const Unit& u, int wr, int wc, int fr, int fq) const {
;         const int row0 = u.pm * 256 + wr * 64 + fr, cw = wc * 32 + 8 * fq; const int pn = u.pn;
;         EPI_ROWS(
;             const float rs = __builtin_amdgcn_rsqf(ss1[row] * (1.f / 1024.f) + EPS);
;             f32x4 v[2][2];
;             _Pragma("unroll") for (int bj = 0; bj < 2; ++bj) { v[bj][0] = acc[ai][bj][m][0] * rs; v[bj][1] = acc[ai][bj][m][1] * rs; }
;             if (pn < 3) {
;                 _Pragma("unroll") for (int bj = 0; bj < 2; ++bj) *(u32x4*)(ZA + (size_t)row * 768 + pn * 256 + bj * 128 + cw) = pack8(v[bj][0], v[bj][1]);
;                 float s = dot8(v[0][0], v[0][1]); if (pn != 1) s += dot8(v[1][0], v[1][1]);
;                 s = red_fq(s); if (fq == 0) unsafeAtomicAdd((pn == 2 ? sskv : ssq) + row, s);
;             } else if (pn < 7) {
;                 _Pragma("unroll") for (int bj = 0; bj < 2; ++bj) *(u32x4*)(ZRX + (size_t)row * 1024 + (pn - 3) * 256 + bj * 128 + cw) = pack8(v[bj][0], v[bj][1]);
;             } else if (pn < 11) {
;                 _Pragma("unroll") for (int bj = 0; bj < 2; ++bj) { _Pragma("unroll") for (int n = 0; n < 2; ++n) _Pragma("unroll") for (int i = 0; i < 4; ++i) v[bj][n][i] = gelu_tanh(v[bj][n][i]);
;                     *(u32x4*)(ZRG + (size_t)row * 1024 + (pn - 7) * 256 + bj * 128 + cw) = pack8(v[bj][0], v[bj][1]); }
;             } else {
;                 _Pragma("unroll") for (int bj = 0; bj < 2; ++bj) { unsigned w[2];
;                     _Pragma("unroll") for (int n = 0; n < 2; ++n) { unsigned q = 0; _Pragma("unroll") for (int i = 0; i < 4; ++i) { const unsigned b = (unsigned)(sigmoidf_(v[bj][n][i]) * 255.f + 0.5f); q |= (b > 255u ? 255u : b) << (8 * i); } w[n] = q; }
;                     *(u32x2*)(ZG8 + (size_t)row * 2048 + (pn - 11) * 256 + bj * 128 + cw) = (u32x2){w[0], w[1]}; }
.LBB0_550:
	s_nop 0
	s_and_b64 vcc, exec, s[10:11]
	s_mov_b64 s[10:11], -1
	s_waitcnt vmcnt(14)
	v_fmamk_f32 v18, v207, 0x3a800000, v155
	v_rsq_f32_e32 v20, v18
	v_add_u32_e32 v18, 0xb0, v140
	s_waitcnt lgkmcnt(0)
	v_ashrrev_i32_e32 v19, 31, v18
	v_pk_mul_f32 v[16:17], v[16:17], v[20:21] op_sel_hi:[1,0]
	v_pk_mul_f32 v[14:15], v[14:15], v[20:21] op_sel_hi:[1,0]
	v_pk_mul_f32 v[12:13], v[12:13], v[20:21] op_sel_hi:[1,0]
	v_pk_mul_f32 v[10:11], v[10:11], v[20:21] op_sel_hi:[1,0]
	v_pk_mul_f32 v[8:9], v[8:9], v[20:21] op_sel_hi:[1,0]
	v_pk_mul_f32 v[6:7], v[6:7], v[20:21] op_sel_hi:[1,0]
	v_pk_mul_f32 v[4:5], v[4:5], v[20:21] op_sel_hi:[1,0]
	v_pk_mul_f32 v[2:3], v[2:3], v[20:21] op_sel_hi:[1,0]
	s_cbranch_vccnz .LBB0_560
	v_lshlrev_b64 v[20:21], 11, v[18:19]
	s_and_b64 vcc, exec, s[12:13]
	s_cbranch_vccnz .LBB0_557
	s_andn2_b64 vcc, exec, s[78:79]
	s_cbranch_vccnz .LBB0_554
	v_mul_f32_e32 v19, 0xbfb8aa3b, v14
	v_mul_f32_e32 v22, 0xbfb8aa3b, v15
	v_exp_f32_e32 v19, v19
	v_exp_f32_e32 v22, v22
	v_mul_f32_e32 v23, 0xbfb8aa3b, v17
	v_exp_f32_e32 v23, v23
	v_add_f32_e32 v19, 1.0, v19
	v_add_f32_e32 v22, 1.0, v22
	v_rcp_f32_e32 v19, v19
	v_rcp_f32_e32 v22, v22
	v_add_f32_e32 v23, 1.0, v23
	v_rcp_f32_e32 v23, v23
	v_fma_f32 v19, v19, s51, 0.5
	v_fma_f32 v22, v22, s51, 0.5
	v_cvt_u32_f32_e32 v19, v19
	v_cvt_u32_f32_e32 v22, v22
	v_fma_f32 v23, v23, s51, 0.5
	v_cvt_u32_f32_e32 v23, v23
	v_min_u32_e32 v19, 0xff, v19
	v_min_u32_e32 v22, 0xff, v22
	v_lshl_or_b32 v19, v22, 8, v19
	v_mul_f32_e32 v22, 0xbfb8aa3b, v16
	v_exp_f32_e32 v22, v22
	v_min_u32_sdwa v23, v23, s58 dst_sel:BYTE_3 dst_unused:UNUSED_PAD src0_sel:DWORD src1_sel:DWORD
	v_mul_f32_e32 v24, 0xbfb8aa3b, v13
	v_exp_f32_e32 v24, v24
	v_add_f32_e32 v22, 1.0, v22
	v_rcp_f32_e32 v22, v22
	v_mul_f32_e32 v26, 0xbfb8aa3b, v5
	v_add_f32_e32 v24, 1.0, v24
	v_rcp_f32_e32 v24, v24
	v_fma_f32 v22, v22, s51, 0.5
	v_cvt_u32_f32_e32 v22, v22
	v_exp_f32_e32 v26, v26
	v_fma_f32 v24, v24, s51, 0.5
	v_cvt_u32_f32_e32 v24, v24
	v_min_u32_sdwa v22, v22, s58 dst_sel:WORD_1 dst_unused:UNUSED_PAD src0_sel:DWORD src1_sel:DWORD
	v_add_f32_e32 v26, 1.0, v26
	v_or3_b32 v22, v19, v22, v23
	v_mul_f32_e32 v19, 0xbfb8aa3b, v10
	v_mul_f32_e32 v23, 0xbfb8aa3b, v11
	v_exp_f32_e32 v19, v19
	v_exp_f32_e32 v23, v23
	v_min_u32_sdwa v24, v24, s58 dst_sel:BYTE_3 dst_unused:UNUSED_PAD src0_sel:DWORD src1_sel:DWORD
	v_rcp_f32_e32 v26, v26
	v_add_f32_e32 v19, 1.0, v19
	v_add_f32_e32 v23, 1.0, v23
	v_rcp_f32_e32 v19, v19
	v_rcp_f32_e32 v23, v23
	v_fma_f32 v26, v26, s51, 0.5
	v_cvt_u32_f32_e32 v26, v26
	v_fma_f32 v19, v19, s51, 0.5
	v_fma_f32 v23, v23, s51, 0.5
	v_cvt_u32_f32_e32 v19, v19
	v_cvt_u32_f32_e32 v23, v23
	v_min_u32_sdwa v26, v26, s58 dst_sel:BYTE_3 dst_unused:UNUSED_PAD src0_sel:DWORD src1_sel:DWORD
	s_mov_b64 s[10:11], 0
	v_min_u32_e32 v19, 0xff, v19
	v_min_u32_e32 v23, 0xff, v23
	v_lshl_or_b32 v19, v23, 8, v19
	v_mul_f32_e32 v23, 0xbfb8aa3b, v12
	v_exp_f32_e32 v23, v23
	s_nop 0
	v_add_f32_e32 v23, 1.0, v23
	v_rcp_f32_e32 v23, v23
	s_nop 0
	v_fma_f32 v23, v23, s51, 0.5
	v_cvt_u32_f32_e32 v23, v23
	v_min_u32_sdwa v23, v23, s58 dst_sel:WORD_1 dst_unused:UNUSED_PAD src0_sel:DWORD src1_sel:DWORD
	s_nop 0
	v_or3_b32 v23, v19, v23, v24
	v_lshl_add_u64 v[24:25], s[22:23], 0, v[20:21]
	v_lshl_add_u64 v[24:25], v[24:25], 0, s[0:1]
	v_lshl_add_u64 v[24:25], v[24:25], 0, v[130:131]
	global_store_dwordx2 v[24:25], v[22:23], off
	v_mul_f32_e32 v19, 0xbfb8aa3b, v6
	v_mul_f32_e32 v22, 0xbfb8aa3b, v7
	v_exp_f32_e32 v19, v19
	v_exp_f32_e32 v22, v22
	v_mul_f32_e32 v23, 0xbfb8aa3b, v9
	v_exp_f32_e32 v23, v23
	v_add_f32_e32 v19, 1.0, v19
	v_add_f32_e32 v22, 1.0, v22
	v_rcp_f32_e32 v19, v19
	v_rcp_f32_e32 v22, v22
	v_add_f32_e32 v23, 1.0, v23
	v_rcp_f32_e32 v23, v23
	v_fma_f32 v19, v19, s51, 0.5
	v_fma_f32 v22, v22, s51, 0.5
	v_cvt_u32_f32_e32 v19, v19
	v_cvt_u32_f32_e32 v22, v22
	v_fma_f32 v23, v23, s51, 0.5
	v_cvt_u32_f32_e32 v23, v23
	v_min_u32_e32 v19, 0xff, v19
	v_min_u32_e32 v22, 0xff, v22
	v_lshl_or_b32 v19, v22, 8, v19
	v_mul_f32_e32 v22, 0xbfb8aa3b, v8
	v_exp_f32_e32 v22, v22
	v_min_u32_sdwa v23, v23, s58 dst_sel:BYTE_3 dst_unused:UNUSED_PAD src0_sel:DWORD src1_sel:DWORD
	v_add_f32_e32 v22, 1.0, v22
	v_rcp_f32_e32 v22, v22
	s_nop 0
	v_fma_f32 v22, v22, s51, 0.5
	v_cvt_u32_f32_e32 v22, v22
	v_min_u32_sdwa v22, v22, s58 dst_sel:WORD_1 dst_unused:UNUSED_PAD src0_sel:DWORD src1_sel:DWORD
	s_nop 0
	v_or3_b32 v22, v19, v22, v23
	v_mul_f32_e32 v19, 0xbfb8aa3b, v2
	v_mul_f32_e32 v23, 0xbfb8aa3b, v3
	v_exp_f32_e32 v19, v19
	v_exp_f32_e32 v23, v23
	v_add_f32_e32 v19, 1.0, v19
	v_add_f32_e32 v23, 1.0, v23
	v_rcp_f32_e32 v19, v19
	v_rcp_f32_e32 v23, v23
	v_fma_f32 v19, v19, s51, 0.5
	v_fma_f32 v23, v23, s51, 0.5
	v_cvt_u32_f32_e32 v19, v19
	v_cvt_u32_f32_e32 v23, v23
	v_min_u32_e32 v19, 0xff, v19
	v_min_u32_e32 v23, 0xff, v23
	v_lshl_or_b32 v19, v23, 8, v19
	v_mul_f32_e32 v23, 0xbfb8aa3b, v4
	v_exp_f32_e32 v23, v23
	s_nop 0
	v_add_f32_e32 v23, 1.0, v23
	v_rcp_f32_e32 v23, v23
	s_nop 0
	v_fma_f32 v23, v23, s51, 0.5
	v_cvt_u32_f32_e32 v23, v23
	v_min_u32_sdwa v23, v23, s58 dst_sel:WORD_1 dst_unused:UNUSED_PAD src0_sel:DWORD src1_sel:DWORD
	s_nop 0
	v_or3_b32 v23, v19, v23, v26
	global_store_dwordx2 v[24:25], v[22:23], off offset:128
